# GEMM units (out-proj, MLP-in, MLP-out): first K-loop iteration peeled; its first K-tile's two waits tolerate the previous unit's 16 output stores (vmcnt 8+16)
# baseline (speedup 1.0000x reference)
.LBB0_121:
	s_lshl_b32 s0, s0, 5
	v_and_b32_e32 v140, 63, v0
	v_and_b32_e32 v7, 48, v0
	v_lshlrev_b32_e32 v8, 6, v0
	s_movk_i32 s9, 0x3c0
	v_lshlrev_b32_e32 v0, 2, v0
	s_and_b32 s53, s0, 0x60
	s_lshl_b32 s52, s1, 6
	s_lshl_b32 s1, s1, 13
	v_and_or_b32 v7, v8, s9, v7
	v_and_b32_e32 v0, 32, v0
	s_lshl_b32 s0, s53, 7
	v_bitop3_b32 v8, v7, s1, v0 bitop3:0xde
	v_bitop3_b32 v141, s0, v7, v0 bitop3:0xf6
	v_lshlrev_b32_e32 v0, 15, v1
	v_and_b32_e32 v0, 0xffff0000, v0
	v_lshl_add_u32 v0, v2, 12, v0
	v_and_b32_e32 v1, 1, v1
	v_lshl_or_b32 v0, v1, 6, v0
	v_lshl_add_u32 v134, v3, 1, v0
	v_lshlrev_b32_e32 v0, 15, v4
	v_and_b32_e32 v0, 0xffff0000, v0
	s_waitcnt vmcnt(8)
	s_barrier
	s_waitcnt vmcnt(6)
	v_lshl_add_u32 v0, v5, 12, v0
	v_and_b32_e32 v1, 1, v4
	v_lshl_or_b32 v0, v1, 6, v0
	v_mov_b32_e32 v135, v193
	v_lshl_add_u32 v136, v6, 1, v0
	v_mov_b32_e32 v137, v193
	s_mov_b32 s54, 0
	v_add_u32_e32 v142, 0, v8
	s_mov_b64 s[28:29], s[4:5]
	s_mov_b64 s[12:13], s[2:3]
	s_barrier
	s_mov_b32 s99, 0

.LBB0_131:
	s_add_i32 s64, s63, -2
	s_add_u32 s2, s2, 0x80080
	s_addc_u32 s3, s3, 0
	s_add_u32 s67, s4, 0x100
	s_addc_u32 s69, s5, 0
	s_mov_b32 s4, 0
	v_add_u32_e32 v138, 0x10000, v141
	ds_read_b128 v[144:147], v138
	ds_read_b128 v[148:151], v138 offset:1024
	ds_read_b128 v[152:155], v138 offset:2048
	ds_read_b128 v[156:159], v138 offset:3072
	ds_read_b128 v[160:163], v142
	ds_read_b128 v[164:167], v142 offset:1024
	ds_read_b128 v[168:171], v142 offset:2048
	ds_read_b128 v[172:175], v142 offset:3072
	ds_read_b128 v[176:179], v142 offset:4096
	ds_read_b128 v[180:183], v142 offset:5120
	ds_read_b128 v[184:187], v142 offset:6144
	ds_read_b128 v[188:191], v142 offset:7168
	v_add_u32_e32 v138, 0x14000, v141
	ds_read_b128 v[194:197], v138
	ds_read_b128 v[198:201], v138 offset:1024
	ds_read_b128 v[202:205], v138 offset:2048
	ds_read_b128 v[206:209], v138 offset:3072
	s_add_i32 s71, s4, 2
	s_add_u32 s5, s2, 0xfff80080
	s_addc_u32 s9, s3, -1
	s_add_i32 s46, 0, 0x10000
	s_cmp_eq_u32 s64, s4
	s_cselect_b32 s4, s28, s67
	s_cselect_b32 s35, s13, s9
	s_cselect_b32 s34, s12, s5
	s_cselect_b32 s5, s29, s69
	v_lshl_add_u64 v[138:139], s[2:3], 0, v[134:135]
	s_add_i32 m0, s40, 0xc000
	s_nop 0
	global_load_lds_dwordx4 v[138:139], off
	v_lshl_add_u64 v[138:139], s[2:3], 0, v[136:137]
	s_add_i32 m0, s40, 0xe000
	s_nop 0
	global_load_lds_dwordx4 v[138:139], off
	s_cmp_eq_u32 s99, 1
	s_cbranch_scc1 .Lrw132_1r
	s_waitcnt vmcnt(8)
	s_branch .Lrw132_1d
.Lrw132_1r:
	s_waitcnt vmcnt(24)
.Lrw132_1d:
	s_waitcnt lgkmcnt(0)
	s_barrier
	s_setprio 1
	v_mfma_f32_16x16x32_bf16 v[124:127], v[144:147], v[160:163], 0
	v_mfma_f32_16x16x32_bf16 v[120:123], v[152:155], v[160:163], 0
	v_mfma_f32_16x16x32_bf16 v[116:119], v[144:147], v[168:171], 0
	v_mfma_f32_16x16x32_bf16 v[108:111], v[152:155], v[168:171], 0
	v_mfma_f32_16x16x32_bf16 v[100:103], v[144:147], v[176:179], 0
	v_mfma_f32_16x16x32_bf16 v[92:95], v[152:155], v[176:179], 0
	v_mfma_f32_16x16x32_bf16 v[84:87], v[144:147], v[184:187], 0
	v_mfma_f32_16x16x32_bf16 v[76:79], v[152:155], v[184:187], 0
	v_mfma_f32_16x16x32_bf16 v[124:127], v[148:151], v[164:167], v[124:127]
	v_mfma_f32_16x16x32_bf16 v[120:123], v[156:159], v[164:167], v[120:123]
	v_mfma_f32_16x16x32_bf16 v[116:119], v[148:151], v[172:175], v[116:119]
	v_mfma_f32_16x16x32_bf16 v[108:111], v[156:159], v[172:175], v[108:111]
	v_mfma_f32_16x16x32_bf16 v[100:103], v[148:151], v[180:183], v[100:103]
	v_mfma_f32_16x16x32_bf16 v[92:95], v[156:159], v[180:183], v[92:95]
	v_mfma_f32_16x16x32_bf16 v[84:87], v[148:151], v[188:191], v[84:87]
	v_mfma_f32_16x16x32_bf16 v[76:79], v[156:159], v[188:191], v[76:79]
	v_mfma_f32_16x16x32_bf16 v[112:115], v[194:197], v[160:163], 0
	v_mfma_f32_16x16x32_bf16 v[104:107], v[202:205], v[160:163], 0
	v_mfma_f32_16x16x32_bf16 v[96:99], v[194:197], v[168:171], 0
	v_mfma_f32_16x16x32_bf16 v[88:91], v[202:205], v[168:171], 0
	v_mfma_f32_16x16x32_bf16 v[80:83], v[194:197], v[176:179], 0
	v_mfma_f32_16x16x32_bf16 v[72:75], v[202:205], v[176:179], 0
	v_mfma_f32_16x16x32_bf16 v[68:71], v[194:197], v[184:187], 0
	v_mfma_f32_16x16x32_bf16 v[64:67], v[202:205], v[184:187], 0
	v_mfma_f32_16x16x32_bf16 v[112:115], v[198:201], v[164:167], v[112:115]
	v_mfma_f32_16x16x32_bf16 v[104:107], v[206:209], v[164:167], v[104:107]
	v_mfma_f32_16x16x32_bf16 v[96:99], v[198:201], v[172:175], v[96:99]
	v_mfma_f32_16x16x32_bf16 v[88:91], v[206:209], v[172:175], v[88:91]
	v_mfma_f32_16x16x32_bf16 v[80:83], v[198:201], v[180:183], v[80:83]
	v_mfma_f32_16x16x32_bf16 v[72:75], v[206:209], v[180:183], v[72:75]
	v_mfma_f32_16x16x32_bf16 v[68:71], v[198:201], v[188:191], v[68:71]
	v_mfma_f32_16x16x32_bf16 v[64:67], v[206:209], v[188:191], v[64:67]
	s_setprio 0
	s_barrier
	ds_read_b128 v[160:163], v142 offset:16384
	ds_read_b128 v[164:167], v142 offset:17408
	ds_read_b128 v[168:171], v142 offset:18432
	ds_read_b128 v[172:175], v142 offset:19456
	ds_read_b128 v[176:179], v142 offset:20480
	ds_read_b128 v[180:183], v142 offset:21504
	ds_read_b128 v[184:187], v142 offset:22528
	ds_read_b128 v[188:191], v142 offset:23552
	s_add_i32 s9, 0, 0x14000
	s_add_i32 s46, s46, s39
	v_lshl_add_u64 v[138:139], s[4:5], 0, v[192:193]
	s_mov_b32 m0, s46
	v_lshl_add_u64 v[210:211], s[4:5], 0, v[132:133]
	global_load_lds_dwordx4 v[138:139], off
	s_add_i32 m0, s46, 0x2000
	s_nop 0
	global_load_lds_dwordx4 v[210:211], off
	s_mov_b32 m0, s40
	v_lshl_add_u64 v[212:213], s[34:35], 0, v[128:129]
	global_load_lds_dwordx4 v[212:213], off
	v_lshl_add_u64 v[214:215], s[34:35], 0, v[130:131]
	s_mov_b32 m0, s41
	s_nop 0
	global_load_lds_dwordx4 v[214:215], off
	s_add_u32 s46, s4, 0x80000
	s_addc_u32 s47, s5, 0
	s_add_i32 s9, s9, s39
	v_lshl_add_u64 v[218:219], s[46:47], 0, v[192:193]
	s_mov_b32 m0, s9
	s_nop 0
	global_load_lds_dwordx4 v[218:219], off
	v_lshl_add_u64 v[220:221], s[46:47], 0, v[132:133]
	s_add_i32 m0, s9, 0x2000
	s_nop 0
	global_load_lds_dwordx4 v[220:221], off
	s_cmp_eq_u32 s99, 1
	s_cbranch_scc1 .Lrw132_2r
	s_waitcnt vmcnt(8)
	s_branch .Lrw132_2d

.Lrw132_2d:
	s_waitcnt lgkmcnt(0)
	s_barrier
	s_setprio 1
	v_mfma_f32_16x16x32_bf16 v[60:63], v[144:147], v[160:163], 0
	v_mfma_f32_16x16x32_bf16 v[56:59], v[152:155], v[160:163], 0
	v_mfma_f32_16x16x32_bf16 v[52:55], v[144:147], v[168:171], 0
	v_mfma_f32_16x16x32_bf16 v[44:47], v[152:155], v[168:171], 0
	v_mfma_f32_16x16x32_bf16 v[36:39], v[144:147], v[176:179], 0
	v_mfma_f32_16x16x32_bf16 v[28:31], v[152:155], v[176:179], 0
	v_mfma_f32_16x16x32_bf16 v[20:23], v[144:147], v[184:187], 0
	v_mfma_f32_16x16x32_bf16 v[12:15], v[152:155], v[184:187], 0
	v_mfma_f32_16x16x32_bf16 v[60:63], v[148:151], v[164:167], v[60:63]
	v_mfma_f32_16x16x32_bf16 v[56:59], v[156:159], v[164:167], v[56:59]
	v_mfma_f32_16x16x32_bf16 v[52:55], v[148:151], v[172:175], v[52:55]
	v_mfma_f32_16x16x32_bf16 v[44:47], v[156:159], v[172:175], v[44:47]
	v_mfma_f32_16x16x32_bf16 v[36:39], v[148:151], v[180:183], v[36:39]
	v_mfma_f32_16x16x32_bf16 v[28:31], v[156:159], v[180:183], v[28:31]
	v_mfma_f32_16x16x32_bf16 v[20:23], v[148:151], v[188:191], v[20:23]
	v_mfma_f32_16x16x32_bf16 v[12:15], v[156:159], v[188:191], v[12:15]
	v_mfma_f32_16x16x32_bf16 v[48:51], v[194:197], v[160:163], 0
	v_mfma_f32_16x16x32_bf16 v[40:43], v[202:205], v[160:163], 0
	v_mfma_f32_16x16x32_bf16 v[32:35], v[194:197], v[168:171], 0
	v_mfma_f32_16x16x32_bf16 v[24:27], v[202:205], v[168:171], 0
	v_mfma_f32_16x16x32_bf16 v[16:19], v[194:197], v[176:179], 0
	v_mfma_f32_16x16x32_bf16 v[8:11], v[202:205], v[176:179], 0
	v_mfma_f32_16x16x32_bf16 v[4:7], v[194:197], v[184:187], 0
	v_mfma_f32_16x16x32_bf16 v[0:3], v[202:205], v[184:187], 0
	v_mfma_f32_16x16x32_bf16 v[48:51], v[198:201], v[164:167], v[48:51]
	v_mfma_f32_16x16x32_bf16 v[40:43], v[206:209], v[164:167], v[40:43]
	v_mfma_f32_16x16x32_bf16 v[32:35], v[198:201], v[172:175], v[32:35]
	v_mfma_f32_16x16x32_bf16 v[24:27], v[206:209], v[172:175], v[24:27]
	v_mfma_f32_16x16x32_bf16 v[16:19], v[198:201], v[180:183], v[16:19]
	v_mfma_f32_16x16x32_bf16 v[8:11], v[206:209], v[180:183], v[8:11]
	v_mfma_f32_16x16x32_bf16 v[4:7], v[198:201], v[188:191], v[4:7]
	v_mfma_f32_16x16x32_bf16 v[0:3], v[206:209], v[188:191], v[0:3]
	s_setprio 0
	s_barrier
	v_add_u32_e32 v143, 0x18000, v141
	ds_read_b128 v[144:147], v143
	ds_read_b128 v[148:151], v143 offset:1024
	ds_read_b128 v[152:155], v143 offset:2048
	ds_read_b128 v[156:159], v143 offset:3072
	ds_read_b128 v[160:163], v142 offset:32768
	ds_read_b128 v[164:167], v142 offset:33792
	ds_read_b128 v[168:171], v142 offset:34816
	ds_read_b128 v[172:175], v142 offset:35840
	ds_read_b128 v[176:179], v142 offset:36864
	ds_read_b128 v[180:183], v142 offset:37888
	ds_read_b128 v[184:187], v142 offset:38912
	ds_read_b128 v[188:191], v142 offset:39936
	v_add_u32_e32 v143, 0x1c000, v141
	ds_read_b128 v[194:197], v143
	ds_read_b128 v[198:201], v143 offset:1024
	ds_read_b128 v[202:205], v143 offset:2048
	ds_read_b128 v[206:209], v143 offset:3072
	s_add_i32 s9, 0, 0x18000
	s_add_u32 s34, s34, 0x80000
	s_addc_u32 s35, s35, 0
	s_mov_b32 m0, s48
	v_lshl_add_u64 v[218:219], s[34:35], 0, v[128:129]
	global_load_lds_dwordx4 v[218:219], off
	v_lshl_add_u64 v[220:221], s[34:35], 0, v[130:131]
	s_mov_b32 m0, s49
	s_nop 0
	global_load_lds_dwordx4 v[220:221], off
	s_waitcnt vmcnt(8)
	s_waitcnt lgkmcnt(0)
	s_barrier
	s_setprio 1
	v_mfma_f32_16x16x32_bf16 v[124:127], v[144:147], v[160:163], v[124:127]
	v_mfma_f32_16x16x32_bf16 v[120:123], v[152:155], v[160:163], v[120:123]
	v_mfma_f32_16x16x32_bf16 v[116:119], v[144:147], v[168:171], v[116:119]
	v_mfma_f32_16x16x32_bf16 v[108:111], v[152:155], v[168:171], v[108:111]
	v_mfma_f32_16x16x32_bf16 v[100:103], v[144:147], v[176:179], v[100:103]
	v_mfma_f32_16x16x32_bf16 v[92:95], v[152:155], v[176:179], v[92:95]
	v_mfma_f32_16x16x32_bf16 v[84:87], v[144:147], v[184:187], v[84:87]
	v_mfma_f32_16x16x32_bf16 v[76:79], v[152:155], v[184:187], v[76:79]
	v_mfma_f32_16x16x32_bf16 v[124:127], v[148:151], v[164:167], v[124:127]
	v_mfma_f32_16x16x32_bf16 v[120:123], v[156:159], v[164:167], v[120:123]
	v_mfma_f32_16x16x32_bf16 v[116:119], v[148:151], v[172:175], v[116:119]
	v_mfma_f32_16x16x32_bf16 v[108:111], v[156:159], v[172:175], v[108:111]
	v_mfma_f32_16x16x32_bf16 v[100:103], v[148:151], v[180:183], v[100:103]
	v_mfma_f32_16x16x32_bf16 v[92:95], v[156:159], v[180:183], v[92:95]
	v_mfma_f32_16x16x32_bf16 v[84:87], v[148:151], v[188:191], v[84:87]
	v_mfma_f32_16x16x32_bf16 v[76:79], v[156:159], v[188:191], v[76:79]
	v_mfma_f32_16x16x32_bf16 v[112:115], v[194:197], v[160:163], v[112:115]
	v_mfma_f32_16x16x32_bf16 v[104:107], v[202:205], v[160:163], v[104:107]
	v_mfma_f32_16x16x32_bf16 v[96:99], v[194:197], v[168:171], v[96:99]
	v_mfma_f32_16x16x32_bf16 v[88:91], v[202:205], v[168:171], v[88:91]
	v_mfma_f32_16x16x32_bf16 v[80:83], v[194:197], v[176:179], v[80:83]
	v_mfma_f32_16x16x32_bf16 v[72:75], v[202:205], v[176:179], v[72:75]
	v_mfma_f32_16x16x32_bf16 v[68:71], v[194:197], v[184:187], v[68:71]
	v_mfma_f32_16x16x32_bf16 v[64:67], v[202:205], v[184:187], v[64:67]
	v_mfma_f32_16x16x32_bf16 v[112:115], v[198:201], v[164:167], v[112:115]
	v_mfma_f32_16x16x32_bf16 v[104:107], v[206:209], v[164:167], v[104:107]
	v_mfma_f32_16x16x32_bf16 v[96:99], v[198:201], v[172:175], v[96:99]
	v_mfma_f32_16x16x32_bf16 v[88:91], v[206:209], v[172:175], v[88:91]
	v_mfma_f32_16x16x32_bf16 v[80:83], v[198:201], v[180:183], v[80:83]
	v_mfma_f32_16x16x32_bf16 v[72:75], v[206:209], v[180:183], v[72:75]
	v_mfma_f32_16x16x32_bf16 v[68:71], v[198:201], v[188:191], v[68:71]
	v_mfma_f32_16x16x32_bf16 v[64:67], v[206:209], v[188:191], v[64:67]
	s_setprio 0
	s_barrier
	ds_read_b128 v[160:163], v142 offset:49152
	ds_read_b128 v[164:167], v142 offset:50176
	ds_read_b128 v[168:171], v142 offset:51200
	ds_read_b128 v[172:175], v142 offset:52224
	ds_read_b128 v[176:179], v142 offset:53248
	ds_read_b128 v[180:183], v142 offset:54272
	ds_read_b128 v[184:187], v142 offset:55296
	ds_read_b128 v[188:191], v142 offset:56320
	s_add_i32 s34, 0, 0x1c000
	s_add_i32 s9, s9, s39
	v_lshl_add_u64 v[138:139], v[138:139], 0, s[72:73]
	s_mov_b32 m0, s9
	s_nop 0
	global_load_lds_dwordx4 v[138:139], off
	v_lshl_add_u64 v[138:139], v[210:211], 0, s[72:73]
	s_add_i32 m0, s9, 0x2000
	s_nop 0
	global_load_lds_dwordx4 v[138:139], off
	s_mov_b32 m0, s50
	v_lshl_add_u64 v[138:139], v[212:213], 0, s[72:73]
	global_load_lds_dwordx4 v[138:139], off
	v_lshl_add_u64 v[138:139], v[214:215], 0, s[72:73]
	s_mov_b32 m0, s51
	s_nop 0
	global_load_lds_dwordx4 v[138:139], off
	s_add_u32 s4, s4, 0x80080
	s_addc_u32 s5, s5, 0
	s_add_i32 s9, s34, s39
	v_lshl_add_u64 v[138:139], s[4:5], 0, v[192:193]
	s_mov_b32 m0, s9
	s_nop 0
	global_load_lds_dwordx4 v[138:139], off
	v_lshl_add_u64 v[138:139], s[4:5], 0, v[132:133]
	s_add_i32 m0, s9, 0x2000
	s_nop 0
	global_load_lds_dwordx4 v[138:139], off
	s_waitcnt vmcnt(8)
	s_waitcnt lgkmcnt(0)
	s_barrier
	s_setprio 1
	v_mfma_f32_16x16x32_bf16 v[60:63], v[144:147], v[160:163], v[60:63]
	v_mfma_f32_16x16x32_bf16 v[56:59], v[152:155], v[160:163], v[56:59]
	v_mfma_f32_16x16x32_bf16 v[52:55], v[144:147], v[168:171], v[52:55]
	v_mfma_f32_16x16x32_bf16 v[44:47], v[152:155], v[168:171], v[44:47]
	v_mfma_f32_16x16x32_bf16 v[36:39], v[144:147], v[176:179], v[36:39]
	v_mfma_f32_16x16x32_bf16 v[28:31], v[152:155], v[176:179], v[28:31]
	v_mfma_f32_16x16x32_bf16 v[20:23], v[144:147], v[184:187], v[20:23]
	v_mfma_f32_16x16x32_bf16 v[12:15], v[152:155], v[184:187], v[12:15]
	v_mfma_f32_16x16x32_bf16 v[60:63], v[148:151], v[164:167], v[60:63]
	v_mfma_f32_16x16x32_bf16 v[56:59], v[156:159], v[164:167], v[56:59]
	v_mfma_f32_16x16x32_bf16 v[52:55], v[148:151], v[172:175], v[52:55]
	v_mfma_f32_16x16x32_bf16 v[44:47], v[156:159], v[172:175], v[44:47]
	v_mfma_f32_16x16x32_bf16 v[36:39], v[148:151], v[180:183], v[36:39]
	v_mfma_f32_16x16x32_bf16 v[28:31], v[156:159], v[180:183], v[28:31]
	v_mfma_f32_16x16x32_bf16 v[20:23], v[148:151], v[188:191], v[20:23]
	v_mfma_f32_16x16x32_bf16 v[12:15], v[156:159], v[188:191], v[12:15]
	v_mfma_f32_16x16x32_bf16 v[48:51], v[194:197], v[160:163], v[48:51]
	v_mfma_f32_16x16x32_bf16 v[40:43], v[202:205], v[160:163], v[40:43]
	v_mfma_f32_16x16x32_bf16 v[32:35], v[194:197], v[168:171], v[32:35]
	v_mfma_f32_16x16x32_bf16 v[24:27], v[202:205], v[168:171], v[24:27]
	v_mfma_f32_16x16x32_bf16 v[16:19], v[194:197], v[176:179], v[16:19]
	v_mfma_f32_16x16x32_bf16 v[8:11], v[202:205], v[176:179], v[8:11]
	v_mfma_f32_16x16x32_bf16 v[4:7], v[194:197], v[184:187], v[4:7]
	v_mfma_f32_16x16x32_bf16 v[0:3], v[202:205], v[184:187], v[0:3]
	v_mfma_f32_16x16x32_bf16 v[48:51], v[198:201], v[164:167], v[48:51]
	v_mfma_f32_16x16x32_bf16 v[40:43], v[206:209], v[164:167], v[40:43]
	v_mfma_f32_16x16x32_bf16 v[32:35], v[198:201], v[172:175], v[32:35]
	v_mfma_f32_16x16x32_bf16 v[24:27], v[206:209], v[172:175], v[24:27]
	v_mfma_f32_16x16x32_bf16 v[16:19], v[198:201], v[180:183], v[16:19]
	v_mfma_f32_16x16x32_bf16 v[8:11], v[206:209], v[180:183], v[8:11]
	v_mfma_f32_16x16x32_bf16 v[4:7], v[198:201], v[188:191], v[4:7]
	v_mfma_f32_16x16x32_bf16 v[0:3], v[206:209], v[188:191], v[0:3]
	s_setprio 0
	s_add_u32 s2, s2, 0x100
	s_addc_u32 s3, s3, 0
	s_add_u32 s67, s67, 0x100
	s_addc_u32 s69, s69, 0
	s_cmp_ge_i32 s71, s63
	s_mov_b32 s4, s71
	s_barrier
	s_cbranch_scc0 .LBB0_132
	s_branch .Lpeel_done_132

.Lpeel_done_132:
	v_sub_co_u32_e64 v138, s[2:3], s66, 1
	s_nop 0
	v_readfirstlane_b32 s64, v138
	s_lshl_b64 s[4:5], s[64:65], 22
	v_readlane_b32 s34, v252, 9
	v_readlane_b32 s35, v252, 10
	s_add_u32 s4, s34, s4
	s_addc_u32 s5, s35, s5
	s_sub_i32 s9, s62, 32
	s_and_b64 s[2:3], s[2:3], exec
	v_readlane_b32 s34, v252, 7
	s_cselect_b32 s2, s62, s9
	v_readlane_b32 s35, v252, 8
	s_cselect_b32 s5, s35, s5
	s_cselect_b32 s4, s34, s4
	s_ashr_i32 s3, s2, 31
	s_lshl_b64 s[2:3], s[2:3], 20
	s_add_u32 s2, s4, s2
	v_mov_b32 v139, v140
	s_addc_u32 s3, s5, s3
	v_ashrrev_i32_e32 v138, 1, v139
	s_lshl_b32 s4, s58, 8
	v_and_b32_e32 v138, -8, v138
	s_or_b32 s4, s4, s53
	v_add_u32_e32 v138, s4, v138
	v_and_or_b32 v144, v139, 15, s52
	v_ashrrev_i32_e32 v139, 31, v138
	v_ashrrev_i32_e32 v145, 31, v144
	v_lshl_add_u64 v[146:147], v[138:139], 1, s[2:3]
	v_lshlrev_b64 v[138:139], 12, v[144:145]
	v_lshl_add_u64 v[138:139], v[146:147], 0, v[138:139]
	v_cvt_pk_bf16_f32 v124, v124, v125
	v_cvt_pk_bf16_f32 v125, v126, v127
	v_cvt_pk_bf16_f32 v126, v120, v121
	v_cvt_pk_bf16_f32 v127, v122, v123
	global_store_dwordx4 v[138:139], v[124:127], off
	v_cvt_pk_bf16_f32 v112, v112, v113
	v_cvt_pk_bf16_f32 v113, v114, v115
	v_cvt_pk_bf16_f32 v114, v104, v105
	v_or_b32_e32 v104, 16, v144
	v_ashrrev_i32_e32 v105, 31, v104
	v_lshlrev_b64 v[104:105], 12, v[104:105]
	v_cvt_pk_bf16_f32 v115, v106, v107
	global_store_dwordx4 v[138:139], v[112:115], off offset:256
	s_mov_b64 s[2:3], 0x80000
	s_mov_b32 s58, s55
	v_lshl_add_u64 v[112:113], v[146:147], 0, v[104:105]
	v_cvt_pk_bf16_f32 v104, v116, v117
	v_cvt_pk_bf16_f32 v105, v118, v119
	v_cvt_pk_bf16_f32 v106, v108, v109
	v_cvt_pk_bf16_f32 v107, v110, v111
	global_store_dwordx4 v[112:113], v[104:107], off
	v_cvt_pk_bf16_f32 v96, v96, v97
	v_cvt_pk_bf16_f32 v97, v98, v99
	v_cvt_pk_bf16_f32 v98, v88, v89
	v_or_b32_e32 v88, 32, v144
	v_ashrrev_i32_e32 v89, 31, v88
	v_lshlrev_b64 v[88:89], 12, v[88:89]
	v_cvt_pk_bf16_f32 v99, v90, v91
	global_store_dwordx4 v[112:113], v[96:99], off offset:256
	s_mov_b32 s62, s14
	s_mov_b32 s66, s15
	v_lshl_add_u64 v[96:97], v[146:147], 0, v[88:89]
	v_cvt_pk_bf16_f32 v88, v100, v101
	v_cvt_pk_bf16_f32 v89, v102, v103
	v_cvt_pk_bf16_f32 v90, v92, v93
	v_cvt_pk_bf16_f32 v91, v94, v95
	global_store_dwordx4 v[96:97], v[88:91], off
	v_cvt_pk_bf16_f32 v80, v80, v81
	v_cvt_pk_bf16_f32 v81, v82, v83
	v_cvt_pk_bf16_f32 v82, v72, v73
	v_or_b32_e32 v72, 48, v144
	v_ashrrev_i32_e32 v73, 31, v72
	v_lshlrev_b64 v[72:73], 12, v[72:73]
	v_cvt_pk_bf16_f32 v83, v74, v75
	global_store_dwordx4 v[96:97], v[80:83], off offset:256
	s_mov_b32 s63, s59
	s_mov_b64 s[4:5], s[28:29]
	v_lshl_add_u64 v[80:81], v[146:147], 0, v[72:73]
	v_cvt_pk_bf16_f32 v72, v84, v85
	v_cvt_pk_bf16_f32 v73, v86, v87
	v_cvt_pk_bf16_f32 v74, v76, v77
	v_cvt_pk_bf16_f32 v75, v78, v79
	global_store_dwordx4 v[80:81], v[72:75], off
	v_cvt_pk_bf16_f32 v68, v68, v69
	v_cvt_pk_bf16_f32 v69, v70, v71
	v_cvt_pk_bf16_f32 v70, v64, v65
	v_lshl_add_u64 v[64:65], v[138:139], 0, s[2:3]
	s_mov_b32 s2, 0x80000
	v_cvt_pk_bf16_f32 v71, v66, v67
	global_store_dwordx4 v[80:81], v[68:71], off offset:256
	v_cvt_pk_bf16_f32 v60, v60, v61
	v_cvt_pk_bf16_f32 v61, v62, v63
	v_cvt_pk_bf16_f32 v62, v56, v57
	v_add_co_u32_e32 v56, vcc, s2, v138
	v_cvt_pk_bf16_f32 v63, v58, v59
	s_mov_b64 s[2:3], 0x90000
	s_nop 0
	v_addc_co_u32_e32 v57, vcc, 0, v139, vcc
	global_store_dwordx4 v[56:57], v[60:63], off
	v_cvt_pk_bf16_f32 v48, v48, v49
	v_cvt_pk_bf16_f32 v49, v50, v51
	v_cvt_pk_bf16_f32 v50, v40, v41
	v_cvt_pk_bf16_f32 v51, v42, v43
	global_store_dwordx4 v[64:65], v[48:51], off offset:256
	v_cvt_pk_bf16_f32 v40, v52, v53
	v_cvt_pk_bf16_f32 v41, v54, v55
	v_cvt_pk_bf16_f32 v42, v44, v45
	v_cvt_pk_bf16_f32 v43, v46, v47
	s_nop 1
	v_lshl_add_u64 v[48:49], v[138:139], 0, s[2:3]
	s_mov_b32 s2, 0x90000
	v_add_co_u32_e32 v44, vcc, s2, v138
	s_mov_b64 s[2:3], 0xa0000
	s_nop 0
	v_addc_co_u32_e32 v45, vcc, 0, v139, vcc
	global_store_dwordx4 v[44:45], v[40:43], off
	v_cvt_pk_bf16_f32 v32, v32, v33
	v_cvt_pk_bf16_f32 v33, v34, v35
	v_cvt_pk_bf16_f32 v34, v24, v25
	v_cvt_pk_bf16_f32 v35, v26, v27
	global_store_dwordx4 v[48:49], v[32:35], off offset:256
	v_cvt_pk_bf16_f32 v24, v36, v37
	v_cvt_pk_bf16_f32 v25, v38, v39
	v_cvt_pk_bf16_f32 v26, v28, v29
	v_cvt_pk_bf16_f32 v27, v30, v31
	s_nop 1
	v_lshl_add_u64 v[32:33], v[138:139], 0, s[2:3]
	s_mov_b32 s2, 0xa0000
	v_add_co_u32_e32 v28, vcc, s2, v138
	s_mov_b64 s[2:3], 0xb0000
	s_nop 0
	v_addc_co_u32_e32 v29, vcc, 0, v139, vcc
	global_store_dwordx4 v[28:29], v[24:27], off
	v_cvt_pk_bf16_f32 v16, v16, v17
	v_cvt_pk_bf16_f32 v17, v18, v19
	v_cvt_pk_bf16_f32 v18, v8, v9
	v_cvt_pk_bf16_f32 v19, v10, v11
	global_store_dwordx4 v[32:33], v[16:19], off offset:256
	v_cvt_pk_bf16_f32 v8, v20, v21
	v_cvt_pk_bf16_f32 v9, v22, v23
	v_cvt_pk_bf16_f32 v10, v12, v13
	v_cvt_pk_bf16_f32 v11, v14, v15
	s_nop 1
	v_lshl_add_u64 v[16:17], v[138:139], 0, s[2:3]
	s_mov_b32 s2, 0xb0000
	v_add_co_u32_e32 v12, vcc, s2, v138
	s_mov_b64 s[2:3], s[12:13]
	s_nop 0
	v_addc_co_u32_e32 v13, vcc, 0, v139, vcc
	s_and_b64 vcc, exec, s[0:1]
	global_store_dwordx4 v[12:13], v[8:11], off
	v_cvt_pk_bf16_f32 v4, v4, v5
	v_cvt_pk_bf16_f32 v5, v6, v7
	v_cvt_pk_bf16_f32 v6, v0, v1
	v_cvt_pk_bf16_f32 v7, v2, v3
	global_store_dwordx4 v[16:17], v[4:7], off offset:256
	s_mov_b32 s99, 1
	s_cbranch_vccz .LBB0_122
	s_waitcnt vmcnt(0)
	s_cmpk_gt_u32 s36, 0xff
	s_cbranch_scc1 .LBB0_136
	s_barrier

.LBB0_231:
	v_and_b32_e32 v140, 63, v0
	s_lshl_b32 s58, s15, 6
	v_and_b32_e32 v7, 48, v0
	s_lshl_b32 s9, s15, 13
	v_lshlrev_b32_e32 v8, 6, v0
	s_movk_i32 s15, 0x3c0
	v_lshlrev_b32_e32 v0, 2, v0
	v_and_or_b32 v7, v8, s15, v7
	v_and_b32_e32 v0, 32, v0
	v_bitop3_b32 v8, v7, s9, v0 bitop3:0xde
	s_lshl_b32 s9, s14, 5
	s_and_b32 s59, s9, 0x60
	s_lshl_b32 s9, s59, 7
	v_bitop3_b32 v141, s9, v7, v0 bitop3:0xf6
	v_lshlrev_b32_e32 v0, 17, v1
	v_and_b32_e32 v0, 0xfffc0000, v0
	v_lshl_add_u32 v0, v2, 14, v0
	v_and_b32_e32 v1, 1, v1
	v_lshl_or_b32 v0, v1, 6, v0
	v_lshl_add_u32 v134, v3, 1, v0
	v_lshlrev_b32_e32 v0, 17, v4
	v_and_b32_e32 v0, 0xfffc0000, v0
	s_waitcnt vmcnt(8)
	s_barrier
	s_waitcnt vmcnt(6)
	v_lshl_add_u32 v0, v5, 14, v0
	v_and_b32_e32 v1, 1, v4
	v_lshl_or_b32 v0, v1, 6, v0
	v_mov_b32_e32 v135, v193
	v_lshl_add_u32 v136, v6, 1, v0
	v_mov_b32_e32 v137, v193
	s_mov_b32 s62, 0
	v_add_u32_e32 v142, 0, v8
	s_mov_b64 s[36:37], s[4:5]
	s_mov_b64 s[28:29], s[2:3]
	s_barrier
	s_mov_b32 s99, 0

.LBB0_241:
	s_add_i32 s64, s71, -2
	s_add_u32 s2, s2, 0x200080
	s_addc_u32 s3, s3, 0
	s_add_u32 s75, s4, 0x100
	s_addc_u32 s78, s5, 0
	s_mov_b32 s4, 0
	v_add_u32_e32 v138, 0x10000, v141
	ds_read_b128 v[144:147], v138
	ds_read_b128 v[148:151], v138 offset:1024
	ds_read_b128 v[152:155], v138 offset:2048
	ds_read_b128 v[156:159], v138 offset:3072
	ds_read_b128 v[160:163], v142
	ds_read_b128 v[164:167], v142 offset:1024
	ds_read_b128 v[168:171], v142 offset:2048
	ds_read_b128 v[172:175], v142 offset:3072
	ds_read_b128 v[176:179], v142 offset:4096
	ds_read_b128 v[180:183], v142 offset:5120
	ds_read_b128 v[184:187], v142 offset:6144
	ds_read_b128 v[188:191], v142 offset:7168
	v_add_u32_e32 v138, 0x14000, v141
	ds_read_b128 v[194:197], v138
	ds_read_b128 v[198:201], v138 offset:1024
	ds_read_b128 v[202:205], v138 offset:2048
	ds_read_b128 v[206:209], v138 offset:3072
	s_add_i32 s79, s4, 2
	s_add_u32 s5, s2, 0xffe00080
	s_addc_u32 s9, s3, -1
	s_add_i32 s46, 0, 0x10000
	s_cmp_eq_u32 s64, s4
	s_cselect_b32 s4, s36, s75
	s_cselect_b32 s39, s29, s9
	s_cselect_b32 s38, s28, s5
	s_cselect_b32 s5, s37, s78
	v_lshl_add_u64 v[138:139], s[2:3], 0, v[134:135]
	s_add_i32 m0, s50, 0xc000
	s_nop 0
	global_load_lds_dwordx4 v[138:139], off
	v_lshl_add_u64 v[138:139], s[2:3], 0, v[136:137]
	s_add_i32 m0, s50, 0xe000
	s_nop 0
	global_load_lds_dwordx4 v[138:139], off
	s_cmp_eq_u32 s99, 1
	s_cbranch_scc1 .Lrw242_1r
	s_waitcnt vmcnt(8)
	s_branch .Lrw242_1d

.Lrw242_1d:
	s_waitcnt lgkmcnt(0)
	s_barrier
	s_setprio 1
	v_mfma_f32_16x16x32_bf16 v[124:127], v[144:147], v[160:163], 0
	v_mfma_f32_16x16x32_bf16 v[120:123], v[152:155], v[160:163], 0
	v_mfma_f32_16x16x32_bf16 v[116:119], v[144:147], v[168:171], 0
	v_mfma_f32_16x16x32_bf16 v[108:111], v[152:155], v[168:171], 0
	v_mfma_f32_16x16x32_bf16 v[100:103], v[144:147], v[176:179], 0
	v_mfma_f32_16x16x32_bf16 v[92:95], v[152:155], v[176:179], 0
	v_mfma_f32_16x16x32_bf16 v[84:87], v[144:147], v[184:187], 0
	v_mfma_f32_16x16x32_bf16 v[76:79], v[152:155], v[184:187], 0
	v_mfma_f32_16x16x32_bf16 v[124:127], v[148:151], v[164:167], v[124:127]
	v_mfma_f32_16x16x32_bf16 v[120:123], v[156:159], v[164:167], v[120:123]
	v_mfma_f32_16x16x32_bf16 v[116:119], v[148:151], v[172:175], v[116:119]
	v_mfma_f32_16x16x32_bf16 v[108:111], v[156:159], v[172:175], v[108:111]
	v_mfma_f32_16x16x32_bf16 v[100:103], v[148:151], v[180:183], v[100:103]
	v_mfma_f32_16x16x32_bf16 v[92:95], v[156:159], v[180:183], v[92:95]
	v_mfma_f32_16x16x32_bf16 v[84:87], v[148:151], v[188:191], v[84:87]
	v_mfma_f32_16x16x32_bf16 v[76:79], v[156:159], v[188:191], v[76:79]
	v_mfma_f32_16x16x32_bf16 v[112:115], v[194:197], v[160:163], 0
	v_mfma_f32_16x16x32_bf16 v[104:107], v[202:205], v[160:163], 0
	v_mfma_f32_16x16x32_bf16 v[96:99], v[194:197], v[168:171], 0
	v_mfma_f32_16x16x32_bf16 v[88:91], v[202:205], v[168:171], 0
	v_mfma_f32_16x16x32_bf16 v[80:83], v[194:197], v[176:179], 0
	v_mfma_f32_16x16x32_bf16 v[72:75], v[202:205], v[176:179], 0
	v_mfma_f32_16x16x32_bf16 v[68:71], v[194:197], v[184:187], 0
	v_mfma_f32_16x16x32_bf16 v[64:67], v[202:205], v[184:187], 0
	v_mfma_f32_16x16x32_bf16 v[112:115], v[198:201], v[164:167], v[112:115]
	v_mfma_f32_16x16x32_bf16 v[104:107], v[206:209], v[164:167], v[104:107]
	v_mfma_f32_16x16x32_bf16 v[96:99], v[198:201], v[172:175], v[96:99]
	v_mfma_f32_16x16x32_bf16 v[88:91], v[206:209], v[172:175], v[88:91]
	v_mfma_f32_16x16x32_bf16 v[80:83], v[198:201], v[180:183], v[80:83]
	v_mfma_f32_16x16x32_bf16 v[72:75], v[206:209], v[180:183], v[72:75]
	v_mfma_f32_16x16x32_bf16 v[68:71], v[198:201], v[188:191], v[68:71]
	v_mfma_f32_16x16x32_bf16 v[64:67], v[206:209], v[188:191], v[64:67]
	s_setprio 0
	s_barrier
	ds_read_b128 v[160:163], v142 offset:16384
	ds_read_b128 v[164:167], v142 offset:17408
	ds_read_b128 v[168:171], v142 offset:18432
	ds_read_b128 v[172:175], v142 offset:19456
	ds_read_b128 v[176:179], v142 offset:20480
	ds_read_b128 v[180:183], v142 offset:21504
	ds_read_b128 v[184:187], v142 offset:22528
	ds_read_b128 v[188:191], v142 offset:23552
	s_add_i32 s9, 0, 0x14000
	s_add_i32 s46, s46, s49
	v_lshl_add_u64 v[138:139], s[4:5], 0, v[192:193]
	s_mov_b32 m0, s46
	v_lshl_add_u64 v[210:211], s[4:5], 0, v[132:133]
	global_load_lds_dwordx4 v[138:139], off
	s_add_i32 m0, s46, 0x2000
	s_nop 0
	global_load_lds_dwordx4 v[210:211], off
	s_mov_b32 m0, s50
	v_lshl_add_u64 v[212:213], s[38:39], 0, v[128:129]
	global_load_lds_dwordx4 v[212:213], off
	v_lshl_add_u64 v[214:215], s[38:39], 0, v[130:131]
	s_mov_b32 m0, s51
	s_nop 0
	global_load_lds_dwordx4 v[214:215], off
	s_add_u32 s46, s4, 0x200000
	s_addc_u32 s47, s5, 0
	s_add_i32 s9, s9, s49
	v_lshl_add_u64 v[218:219], s[46:47], 0, v[192:193]
	s_mov_b32 m0, s9
	s_nop 0
	global_load_lds_dwordx4 v[218:219], off
	v_lshl_add_u64 v[220:221], s[46:47], 0, v[132:133]
	s_add_i32 m0, s9, 0x2000
	s_nop 0
	global_load_lds_dwordx4 v[220:221], off
	s_cmp_eq_u32 s99, 1
	s_cbranch_scc1 .Lrw242_2r
	s_waitcnt vmcnt(8)
	s_branch .Lrw242_2d

.Lrw242_2d:
	s_waitcnt lgkmcnt(0)
	s_barrier
	s_setprio 1
	v_mfma_f32_16x16x32_bf16 v[60:63], v[144:147], v[160:163], 0
	v_mfma_f32_16x16x32_bf16 v[56:59], v[152:155], v[160:163], 0
	v_mfma_f32_16x16x32_bf16 v[52:55], v[144:147], v[168:171], 0
	v_mfma_f32_16x16x32_bf16 v[44:47], v[152:155], v[168:171], 0
	v_mfma_f32_16x16x32_bf16 v[36:39], v[144:147], v[176:179], 0
	v_mfma_f32_16x16x32_bf16 v[28:31], v[152:155], v[176:179], 0
	v_mfma_f32_16x16x32_bf16 v[20:23], v[144:147], v[184:187], 0
	v_mfma_f32_16x16x32_bf16 v[12:15], v[152:155], v[184:187], 0
	v_mfma_f32_16x16x32_bf16 v[60:63], v[148:151], v[164:167], v[60:63]
	v_mfma_f32_16x16x32_bf16 v[56:59], v[156:159], v[164:167], v[56:59]
	v_mfma_f32_16x16x32_bf16 v[52:55], v[148:151], v[172:175], v[52:55]
	v_mfma_f32_16x16x32_bf16 v[44:47], v[156:159], v[172:175], v[44:47]
	v_mfma_f32_16x16x32_bf16 v[36:39], v[148:151], v[180:183], v[36:39]
	v_mfma_f32_16x16x32_bf16 v[28:31], v[156:159], v[180:183], v[28:31]
	v_mfma_f32_16x16x32_bf16 v[20:23], v[148:151], v[188:191], v[20:23]
	v_mfma_f32_16x16x32_bf16 v[12:15], v[156:159], v[188:191], v[12:15]
	v_mfma_f32_16x16x32_bf16 v[48:51], v[194:197], v[160:163], 0
	v_mfma_f32_16x16x32_bf16 v[40:43], v[202:205], v[160:163], 0
	v_mfma_f32_16x16x32_bf16 v[32:35], v[194:197], v[168:171], 0
	v_mfma_f32_16x16x32_bf16 v[24:27], v[202:205], v[168:171], 0
	v_mfma_f32_16x16x32_bf16 v[16:19], v[194:197], v[176:179], 0
	v_mfma_f32_16x16x32_bf16 v[8:11], v[202:205], v[176:179], 0
	v_mfma_f32_16x16x32_bf16 v[4:7], v[194:197], v[184:187], 0
	v_mfma_f32_16x16x32_bf16 v[0:3], v[202:205], v[184:187], 0
	v_mfma_f32_16x16x32_bf16 v[48:51], v[198:201], v[164:167], v[48:51]
	v_mfma_f32_16x16x32_bf16 v[40:43], v[206:209], v[164:167], v[40:43]
	v_mfma_f32_16x16x32_bf16 v[32:35], v[198:201], v[172:175], v[32:35]
	v_mfma_f32_16x16x32_bf16 v[24:27], v[206:209], v[172:175], v[24:27]
	v_mfma_f32_16x16x32_bf16 v[16:19], v[198:201], v[180:183], v[16:19]
	v_mfma_f32_16x16x32_bf16 v[8:11], v[206:209], v[180:183], v[8:11]
	v_mfma_f32_16x16x32_bf16 v[4:7], v[198:201], v[188:191], v[4:7]
	v_mfma_f32_16x16x32_bf16 v[0:3], v[206:209], v[188:191], v[0:3]
	s_setprio 0
	s_barrier
	v_add_u32_e32 v143, 0x18000, v141
	ds_read_b128 v[144:147], v143
	ds_read_b128 v[148:151], v143 offset:1024
	ds_read_b128 v[152:155], v143 offset:2048
	ds_read_b128 v[156:159], v143 offset:3072
	ds_read_b128 v[160:163], v142 offset:32768
	ds_read_b128 v[164:167], v142 offset:33792
	ds_read_b128 v[168:171], v142 offset:34816
	ds_read_b128 v[172:175], v142 offset:35840
	ds_read_b128 v[176:179], v142 offset:36864
	ds_read_b128 v[180:183], v142 offset:37888
	ds_read_b128 v[184:187], v142 offset:38912
	ds_read_b128 v[188:191], v142 offset:39936
	v_add_u32_e32 v143, 0x1c000, v141
	ds_read_b128 v[194:197], v143
	ds_read_b128 v[198:201], v143 offset:1024
	ds_read_b128 v[202:205], v143 offset:2048
	ds_read_b128 v[206:209], v143 offset:3072
	s_add_i32 s9, 0, 0x18000
	s_add_u32 s38, s38, 0x200000
	s_addc_u32 s39, s39, 0
	s_mov_b32 m0, s52
	v_lshl_add_u64 v[218:219], s[38:39], 0, v[128:129]
	global_load_lds_dwordx4 v[218:219], off
	v_lshl_add_u64 v[220:221], s[38:39], 0, v[130:131]
	s_mov_b32 m0, s53
	s_nop 0
	global_load_lds_dwordx4 v[220:221], off
	s_waitcnt vmcnt(8)
	s_waitcnt lgkmcnt(0)
	s_barrier
	s_setprio 1
	v_mfma_f32_16x16x32_bf16 v[124:127], v[144:147], v[160:163], v[124:127]
	v_mfma_f32_16x16x32_bf16 v[120:123], v[152:155], v[160:163], v[120:123]
	v_mfma_f32_16x16x32_bf16 v[116:119], v[144:147], v[168:171], v[116:119]
	v_mfma_f32_16x16x32_bf16 v[108:111], v[152:155], v[168:171], v[108:111]
	v_mfma_f32_16x16x32_bf16 v[100:103], v[144:147], v[176:179], v[100:103]
	v_mfma_f32_16x16x32_bf16 v[92:95], v[152:155], v[176:179], v[92:95]
	v_mfma_f32_16x16x32_bf16 v[84:87], v[144:147], v[184:187], v[84:87]
	v_mfma_f32_16x16x32_bf16 v[76:79], v[152:155], v[184:187], v[76:79]
	v_mfma_f32_16x16x32_bf16 v[124:127], v[148:151], v[164:167], v[124:127]
	v_mfma_f32_16x16x32_bf16 v[120:123], v[156:159], v[164:167], v[120:123]
	v_mfma_f32_16x16x32_bf16 v[116:119], v[148:151], v[172:175], v[116:119]
	v_mfma_f32_16x16x32_bf16 v[108:111], v[156:159], v[172:175], v[108:111]
	v_mfma_f32_16x16x32_bf16 v[100:103], v[148:151], v[180:183], v[100:103]
	v_mfma_f32_16x16x32_bf16 v[92:95], v[156:159], v[180:183], v[92:95]
	v_mfma_f32_16x16x32_bf16 v[84:87], v[148:151], v[188:191], v[84:87]
	v_mfma_f32_16x16x32_bf16 v[76:79], v[156:159], v[188:191], v[76:79]
	v_mfma_f32_16x16x32_bf16 v[112:115], v[194:197], v[160:163], v[112:115]
	v_mfma_f32_16x16x32_bf16 v[104:107], v[202:205], v[160:163], v[104:107]
	v_mfma_f32_16x16x32_bf16 v[96:99], v[194:197], v[168:171], v[96:99]
	v_mfma_f32_16x16x32_bf16 v[88:91], v[202:205], v[168:171], v[88:91]
	v_mfma_f32_16x16x32_bf16 v[80:83], v[194:197], v[176:179], v[80:83]
	v_mfma_f32_16x16x32_bf16 v[72:75], v[202:205], v[176:179], v[72:75]
	v_mfma_f32_16x16x32_bf16 v[68:71], v[194:197], v[184:187], v[68:71]
	v_mfma_f32_16x16x32_bf16 v[64:67], v[202:205], v[184:187], v[64:67]
	v_mfma_f32_16x16x32_bf16 v[112:115], v[198:201], v[164:167], v[112:115]
	v_mfma_f32_16x16x32_bf16 v[104:107], v[206:209], v[164:167], v[104:107]
	v_mfma_f32_16x16x32_bf16 v[96:99], v[198:201], v[172:175], v[96:99]
	v_mfma_f32_16x16x32_bf16 v[88:91], v[206:209], v[172:175], v[88:91]
	v_mfma_f32_16x16x32_bf16 v[80:83], v[198:201], v[180:183], v[80:83]
	v_mfma_f32_16x16x32_bf16 v[72:75], v[206:209], v[180:183], v[72:75]
	v_mfma_f32_16x16x32_bf16 v[68:71], v[198:201], v[188:191], v[68:71]
	v_mfma_f32_16x16x32_bf16 v[64:67], v[206:209], v[188:191], v[64:67]
	s_setprio 0
	s_barrier
	ds_read_b128 v[160:163], v142 offset:49152
	ds_read_b128 v[164:167], v142 offset:50176
	ds_read_b128 v[168:171], v142 offset:51200
	ds_read_b128 v[172:175], v142 offset:52224
	ds_read_b128 v[176:179], v142 offset:53248
	ds_read_b128 v[180:183], v142 offset:54272
	ds_read_b128 v[184:187], v142 offset:55296
	ds_read_b128 v[188:191], v142 offset:56320
	s_add_i32 s38, 0, 0x1c000
	s_add_i32 s9, s9, s49
	v_lshl_add_u64 v[138:139], v[138:139], 0, s[72:73]
	s_mov_b32 m0, s9
	s_nop 0
	global_load_lds_dwordx4 v[138:139], off
	v_lshl_add_u64 v[138:139], v[210:211], 0, s[72:73]
	s_add_i32 m0, s9, 0x2000
	s_nop 0
	global_load_lds_dwordx4 v[138:139], off
	s_mov_b32 m0, s54
	v_lshl_add_u64 v[138:139], v[212:213], 0, s[72:73]
	global_load_lds_dwordx4 v[138:139], off
	v_lshl_add_u64 v[138:139], v[214:215], 0, s[72:73]
	s_mov_b32 m0, s55
	s_nop 0
	global_load_lds_dwordx4 v[138:139], off
	s_add_u32 s4, s4, 0x200080
	s_addc_u32 s5, s5, 0
	s_add_i32 s9, s38, s49
	v_lshl_add_u64 v[138:139], s[4:5], 0, v[192:193]
	s_mov_b32 m0, s9
	s_nop 0
	global_load_lds_dwordx4 v[138:139], off
	v_lshl_add_u64 v[138:139], s[4:5], 0, v[132:133]
	s_add_i32 m0, s9, 0x2000
	s_nop 0
	global_load_lds_dwordx4 v[138:139], off
	s_waitcnt vmcnt(8)
	s_waitcnt lgkmcnt(0)
	s_barrier
	s_setprio 1
	v_mfma_f32_16x16x32_bf16 v[60:63], v[144:147], v[160:163], v[60:63]
	v_mfma_f32_16x16x32_bf16 v[56:59], v[152:155], v[160:163], v[56:59]
	v_mfma_f32_16x16x32_bf16 v[52:55], v[144:147], v[168:171], v[52:55]
	v_mfma_f32_16x16x32_bf16 v[44:47], v[152:155], v[168:171], v[44:47]
	v_mfma_f32_16x16x32_bf16 v[36:39], v[144:147], v[176:179], v[36:39]
	v_mfma_f32_16x16x32_bf16 v[28:31], v[152:155], v[176:179], v[28:31]
	v_mfma_f32_16x16x32_bf16 v[20:23], v[144:147], v[184:187], v[20:23]
	v_mfma_f32_16x16x32_bf16 v[12:15], v[152:155], v[184:187], v[12:15]
	v_mfma_f32_16x16x32_bf16 v[60:63], v[148:151], v[164:167], v[60:63]
	v_mfma_f32_16x16x32_bf16 v[56:59], v[156:159], v[164:167], v[56:59]
	v_mfma_f32_16x16x32_bf16 v[52:55], v[148:151], v[172:175], v[52:55]
	v_mfma_f32_16x16x32_bf16 v[44:47], v[156:159], v[172:175], v[44:47]
	v_mfma_f32_16x16x32_bf16 v[36:39], v[148:151], v[180:183], v[36:39]
	v_mfma_f32_16x16x32_bf16 v[28:31], v[156:159], v[180:183], v[28:31]
	v_mfma_f32_16x16x32_bf16 v[20:23], v[148:151], v[188:191], v[20:23]
	v_mfma_f32_16x16x32_bf16 v[12:15], v[156:159], v[188:191], v[12:15]
	v_mfma_f32_16x16x32_bf16 v[48:51], v[194:197], v[160:163], v[48:51]
	v_mfma_f32_16x16x32_bf16 v[40:43], v[202:205], v[160:163], v[40:43]
	v_mfma_f32_16x16x32_bf16 v[32:35], v[194:197], v[168:171], v[32:35]
	v_mfma_f32_16x16x32_bf16 v[24:27], v[202:205], v[168:171], v[24:27]
	v_mfma_f32_16x16x32_bf16 v[16:19], v[194:197], v[176:179], v[16:19]
	v_mfma_f32_16x16x32_bf16 v[8:11], v[202:205], v[176:179], v[8:11]
	v_mfma_f32_16x16x32_bf16 v[4:7], v[194:197], v[184:187], v[4:7]
	v_mfma_f32_16x16x32_bf16 v[0:3], v[202:205], v[184:187], v[0:3]
	v_mfma_f32_16x16x32_bf16 v[48:51], v[198:201], v[164:167], v[48:51]
	v_mfma_f32_16x16x32_bf16 v[40:43], v[206:209], v[164:167], v[40:43]
	v_mfma_f32_16x16x32_bf16 v[32:35], v[198:201], v[172:175], v[32:35]
	v_mfma_f32_16x16x32_bf16 v[24:27], v[206:209], v[172:175], v[24:27]
	v_mfma_f32_16x16x32_bf16 v[16:19], v[198:201], v[180:183], v[16:19]
	v_mfma_f32_16x16x32_bf16 v[8:11], v[206:209], v[180:183], v[8:11]
	v_mfma_f32_16x16x32_bf16 v[4:7], v[198:201], v[188:191], v[4:7]
	v_mfma_f32_16x16x32_bf16 v[0:3], v[206:209], v[188:191], v[0:3]
	s_setprio 0
	s_add_u32 s2, s2, 0x100
	s_addc_u32 s3, s3, 0
	s_add_u32 s75, s75, 0x100
	s_addc_u32 s78, s78, 0
	s_cmp_ge_i32 s79, s71
	s_mov_b32 s4, s79
	s_barrier
	s_cbranch_scc0 .LBB0_242
	s_branch .Lpeel_done_242

.Lpeel_done_242:
	v_sub_co_u32_e64 v138, s[2:3], s74, 1
	s_nop 0
	v_readfirstlane_b32 s64, v138
	s_lshl_b64 s[4:5], s[64:65], 22
	v_readlane_b32 s38, v252, 9
	v_readlane_b32 s39, v252, 10
	s_add_u32 s4, s38, s4
	s_addc_u32 s5, s39, s5
	s_sub_i32 s9, s69, 32
	s_and_b64 s[2:3], s[2:3], exec
	v_readlane_b32 s38, v252, 7
	s_cselect_b32 s2, s69, s9
	v_readlane_b32 s39, v252, 8
	s_cselect_b32 s5, s39, s5
	s_cselect_b32 s4, s38, s4
	s_ashr_i32 s3, s2, 31
	s_lshl_b64 s[2:3], s[2:3], 20
	s_add_u32 s2, s4, s2
	v_mov_b32 v139, v140
	s_addc_u32 s3, s5, s3
	v_ashrrev_i32_e32 v138, 1, v139
	s_lshl_b32 s4, s66, 8
	v_and_b32_e32 v138, -8, v138
	s_or_b32 s4, s4, s59
	v_add_u32_e32 v138, s4, v138
	v_and_or_b32 v144, v139, 15, s58
	v_ashrrev_i32_e32 v139, 31, v138
	v_ashrrev_i32_e32 v145, 31, v144
	v_lshl_add_u64 v[146:147], v[138:139], 1, s[2:3]
	v_lshlrev_b64 v[138:139], 12, v[144:145]
	v_lshl_add_u64 v[138:139], v[146:147], 0, v[138:139]
	v_cvt_pk_bf16_f32 v124, v124, v125
	v_cvt_pk_bf16_f32 v125, v126, v127
	v_cvt_pk_bf16_f32 v126, v120, v121
	v_cvt_pk_bf16_f32 v127, v122, v123
	global_store_dwordx4 v[138:139], v[124:127], off
	v_cvt_pk_bf16_f32 v112, v112, v113
	v_cvt_pk_bf16_f32 v113, v114, v115
	v_cvt_pk_bf16_f32 v114, v104, v105
	v_or_b32_e32 v104, 16, v144
	v_ashrrev_i32_e32 v105, 31, v104
	v_lshlrev_b64 v[104:105], 12, v[104:105]
	v_cvt_pk_bf16_f32 v115, v106, v107
	global_store_dwordx4 v[138:139], v[112:115], off offset:256
	s_mov_b64 s[2:3], 0x80000
	s_mov_b32 s66, s63
	v_lshl_add_u64 v[112:113], v[146:147], 0, v[104:105]
	v_cvt_pk_bf16_f32 v104, v116, v117
	v_cvt_pk_bf16_f32 v105, v118, v119
	v_cvt_pk_bf16_f32 v106, v108, v109
	v_cvt_pk_bf16_f32 v107, v110, v111
	global_store_dwordx4 v[112:113], v[104:107], off
	v_cvt_pk_bf16_f32 v96, v96, v97
	v_cvt_pk_bf16_f32 v97, v98, v99
	v_cvt_pk_bf16_f32 v98, v88, v89
	v_or_b32_e32 v88, 32, v144
	v_ashrrev_i32_e32 v89, 31, v88
	v_lshlrev_b64 v[88:89], 12, v[88:89]
	v_cvt_pk_bf16_f32 v99, v90, v91
	global_store_dwordx4 v[112:113], v[96:99], off offset:256
	s_mov_b32 s69, s34
	s_mov_b32 s74, s35
	v_lshl_add_u64 v[96:97], v[146:147], 0, v[88:89]
	v_cvt_pk_bf16_f32 v88, v100, v101
	v_cvt_pk_bf16_f32 v89, v102, v103
	v_cvt_pk_bf16_f32 v90, v92, v93
	v_cvt_pk_bf16_f32 v91, v94, v95
	global_store_dwordx4 v[96:97], v[88:91], off
	v_cvt_pk_bf16_f32 v80, v80, v81
	v_cvt_pk_bf16_f32 v81, v82, v83
	v_cvt_pk_bf16_f32 v82, v72, v73
	v_or_b32_e32 v72, 48, v144
	v_ashrrev_i32_e32 v73, 31, v72
	v_lshlrev_b64 v[72:73], 12, v[72:73]
	v_cvt_pk_bf16_f32 v83, v74, v75
	global_store_dwordx4 v[96:97], v[80:83], off offset:256
	s_mov_b32 s71, s67
	s_mov_b64 s[4:5], s[36:37]
	v_lshl_add_u64 v[80:81], v[146:147], 0, v[72:73]
	v_cvt_pk_bf16_f32 v72, v84, v85
	v_cvt_pk_bf16_f32 v73, v86, v87
	v_cvt_pk_bf16_f32 v74, v76, v77
	v_cvt_pk_bf16_f32 v75, v78, v79
	global_store_dwordx4 v[80:81], v[72:75], off
	v_cvt_pk_bf16_f32 v68, v68, v69
	v_cvt_pk_bf16_f32 v69, v70, v71
	v_cvt_pk_bf16_f32 v70, v64, v65
	v_lshl_add_u64 v[64:65], v[138:139], 0, s[2:3]
	s_mov_b32 s2, 0x80000
	v_cvt_pk_bf16_f32 v71, v66, v67
	global_store_dwordx4 v[80:81], v[68:71], off offset:256
	v_cvt_pk_bf16_f32 v60, v60, v61
	v_cvt_pk_bf16_f32 v61, v62, v63
	v_cvt_pk_bf16_f32 v62, v56, v57
	v_add_co_u32_e32 v56, vcc, s2, v138
	v_cvt_pk_bf16_f32 v63, v58, v59
	s_mov_b64 s[2:3], 0x90000
	s_nop 0
	v_addc_co_u32_e32 v57, vcc, 0, v139, vcc
	global_store_dwordx4 v[56:57], v[60:63], off
	v_cvt_pk_bf16_f32 v48, v48, v49
	v_cvt_pk_bf16_f32 v49, v50, v51
	v_cvt_pk_bf16_f32 v50, v40, v41
	v_cvt_pk_bf16_f32 v51, v42, v43
	global_store_dwordx4 v[64:65], v[48:51], off offset:256
	v_cvt_pk_bf16_f32 v40, v52, v53
	v_cvt_pk_bf16_f32 v41, v54, v55
	v_cvt_pk_bf16_f32 v42, v44, v45
	v_cvt_pk_bf16_f32 v43, v46, v47
	s_mov_b64 s[78:79], 0x2000
	s_nop 0
	v_lshl_add_u64 v[48:49], v[138:139], 0, s[2:3]
	s_mov_b32 s2, 0x90000
	v_add_co_u32_e32 v44, vcc, s2, v138
	s_mov_b64 s[2:3], 0xa0000
	s_nop 0
	v_addc_co_u32_e32 v45, vcc, 0, v139, vcc
	global_store_dwordx4 v[44:45], v[40:43], off
	v_cvt_pk_bf16_f32 v32, v32, v33
	v_cvt_pk_bf16_f32 v33, v34, v35
	v_cvt_pk_bf16_f32 v34, v24, v25
	v_cvt_pk_bf16_f32 v35, v26, v27
	global_store_dwordx4 v[48:49], v[32:35], off offset:256
	v_cvt_pk_bf16_f32 v24, v36, v37
	v_cvt_pk_bf16_f32 v25, v38, v39
	v_cvt_pk_bf16_f32 v26, v28, v29
	v_cvt_pk_bf16_f32 v27, v30, v31
	s_nop 1
	v_lshl_add_u64 v[32:33], v[138:139], 0, s[2:3]
	s_mov_b32 s2, 0xa0000
	v_add_co_u32_e32 v28, vcc, s2, v138
	s_mov_b64 s[2:3], 0xb0000
	s_nop 0
	v_addc_co_u32_e32 v29, vcc, 0, v139, vcc
	global_store_dwordx4 v[28:29], v[24:27], off
	v_cvt_pk_bf16_f32 v16, v16, v17
	v_cvt_pk_bf16_f32 v17, v18, v19
	v_cvt_pk_bf16_f32 v18, v8, v9
	v_cvt_pk_bf16_f32 v19, v10, v11
	global_store_dwordx4 v[32:33], v[16:19], off offset:256
	v_cvt_pk_bf16_f32 v8, v20, v21
	v_cvt_pk_bf16_f32 v9, v22, v23
	v_cvt_pk_bf16_f32 v10, v12, v13
	v_cvt_pk_bf16_f32 v11, v14, v15
	s_nop 1
	v_lshl_add_u64 v[16:17], v[138:139], 0, s[2:3]
	s_mov_b32 s2, 0xb0000
	v_add_co_u32_e32 v12, vcc, s2, v138
	s_mov_b64 s[2:3], s[28:29]
	s_nop 0
	v_addc_co_u32_e32 v13, vcc, 0, v139, vcc
	s_and_b64 vcc, exec, s[14:15]
	global_store_dwordx4 v[12:13], v[8:11], off
	v_cvt_pk_bf16_f32 v4, v4, v5
	v_cvt_pk_bf16_f32 v5, v6, v7
	v_cvt_pk_bf16_f32 v6, v0, v1
	v_cvt_pk_bf16_f32 v7, v2, v3
	global_store_dwordx4 v[16:17], v[4:7], off offset:256
	s_mov_b32 s99, 1
	s_cbranch_vccz .LBB0_232
	s_waitcnt vmcnt(0)
	s_cmpk_gt_u32 s40, 0xff
	s_cbranch_scc1 .LBB0_246
	s_barrier

.LBB0_252:
	v_and_b32_e32 v140, 63, v0
	v_and_b32_e32 v7, 48, v0
	v_lshlrev_b32_e32 v8, 6, v0
	s_movk_i32 s1, 0x3c0
	v_lshlrev_b32_e32 v0, 2, v0
	s_sext_i32_i16 s67, s0
	s_lshl_b32 s0, s15, 13
	v_and_or_b32 v7, v8, s1, v7
	v_and_b32_e32 v0, 32, v0
	v_bitop3_b32 v8, v7, s0, v0 bitop3:0xde
	s_lshl_b32 s0, s14, 5
	s_and_b32 s64, s0, 0x60
	s_lshl_b32 s0, s64, 7
	v_bitop3_b32 v141, s0, v7, v0 bitop3:0xf6
	v_lshlrev_b32_e32 v0, 15, v5
	v_and_b32_e32 v0, 0xffff0000, v0
	v_lshl_add_u32 v0, v4, 12, v0
	v_and_b32_e32 v4, 1, v5
	v_lshl_or_b32 v0, v4, 6, v0
	v_lshl_add_u32 v134, v6, 1, v0
	v_lshlrev_b32_e32 v0, 15, v1
	v_and_b32_e32 v0, 0xffff0000, v0
	s_waitcnt vmcnt(8)
	s_barrier
	s_waitcnt vmcnt(6)
	v_lshl_add_u32 v0, v2, 12, v0
	v_and_b32_e32 v1, 1, v1
	v_lshl_or_b32 v0, v1, 6, v0
	s_lshl_b32 s63, s15, 6
	v_mov_b32_e32 v135, v193
	v_lshl_add_u32 v136, v3, 1, v0
	v_mov_b32_e32 v137, v193
	s_mov_b32 s66, 0
	v_add_u32_e32 v142, 0, v8
	s_mov_b64 s[36:37], s[4:5]
	s_mov_b64 s[34:35], s[2:3]
	s_barrier
	s_mov_b32 s99, 0

.LBB0_255:
	s_add_u32 s2, s2, 0x80080
	s_addc_u32 s3, s3, 0
	s_add_u32 s15, s4, 0x100
	s_addc_u32 s29, s5, 0
	s_mov_b32 s69, -2
	v_add_u32_e32 v138, 0x10000, v141
	ds_read_b128 v[144:147], v138
	ds_read_b128 v[148:151], v138 offset:1024
	ds_read_b128 v[152:155], v138 offset:2048
	ds_read_b128 v[156:159], v138 offset:3072
	ds_read_b128 v[160:163], v142
	ds_read_b128 v[164:167], v142 offset:1024
	ds_read_b128 v[168:171], v142 offset:2048
	ds_read_b128 v[172:175], v142 offset:3072
	ds_read_b128 v[176:179], v142 offset:4096
	ds_read_b128 v[180:183], v142 offset:5120
	ds_read_b128 v[184:187], v142 offset:6144
	ds_read_b128 v[188:191], v142 offset:7168
	v_add_u32_e32 v138, 0x14000, v141
	ds_read_b128 v[194:197], v138
	ds_read_b128 v[198:201], v138 offset:1024
	ds_read_b128 v[202:205], v138 offset:2048
	ds_read_b128 v[206:209], v138 offset:3072
	s_add_u32 s4, s2, 0xfff80080
	s_addc_u32 s5, s3, -1
	s_add_i32 s9, 0, 0x10000
	s_cmp_eq_u32 s69, 28
	s_cselect_b32 s49, s35, s5
	s_cselect_b32 s48, s34, s4
	s_cselect_b32 s5, s37, s29
	s_cselect_b32 s4, s36, s15
	v_lshl_add_u64 v[138:139], s[2:3], 0, v[134:135]
	s_add_i32 m0, s39, 0xc000
	s_nop 0
	global_load_lds_dwordx4 v[138:139], off
	v_lshl_add_u64 v[138:139], s[2:3], 0, v[136:137]
	s_add_i32 m0, s39, 0xe000
	s_nop 0
	global_load_lds_dwordx4 v[138:139], off
	s_cmp_eq_u32 s99, 1
	s_cbranch_scc1 .Lrw256_1r
	s_waitcnt vmcnt(8)
	s_branch .Lrw256_1d

.Lrw256_1d:
	s_waitcnt lgkmcnt(0)
	s_barrier
	s_setprio 1
	v_mfma_f32_16x16x32_bf16 v[124:127], v[144:147], v[160:163], 0
	v_mfma_f32_16x16x32_bf16 v[120:123], v[152:155], v[160:163], 0
	v_mfma_f32_16x16x32_bf16 v[108:111], v[144:147], v[168:171], 0
	v_mfma_f32_16x16x32_bf16 v[104:107], v[152:155], v[168:171], 0
	v_mfma_f32_16x16x32_bf16 v[92:95], v[144:147], v[176:179], 0
	v_mfma_f32_16x16x32_bf16 v[88:91], v[152:155], v[176:179], 0
	v_mfma_f32_16x16x32_bf16 v[76:79], v[144:147], v[184:187], 0
	v_mfma_f32_16x16x32_bf16 v[72:75], v[152:155], v[184:187], 0
	v_mfma_f32_16x16x32_bf16 v[124:127], v[148:151], v[164:167], v[124:127]
	v_mfma_f32_16x16x32_bf16 v[120:123], v[156:159], v[164:167], v[120:123]
	v_mfma_f32_16x16x32_bf16 v[108:111], v[148:151], v[172:175], v[108:111]
	v_mfma_f32_16x16x32_bf16 v[104:107], v[156:159], v[172:175], v[104:107]
	v_mfma_f32_16x16x32_bf16 v[92:95], v[148:151], v[180:183], v[92:95]
	v_mfma_f32_16x16x32_bf16 v[88:91], v[156:159], v[180:183], v[88:91]
	v_mfma_f32_16x16x32_bf16 v[76:79], v[148:151], v[188:191], v[76:79]
	v_mfma_f32_16x16x32_bf16 v[72:75], v[156:159], v[188:191], v[72:75]
	v_mfma_f32_16x16x32_bf16 v[116:119], v[194:197], v[160:163], 0
	v_mfma_f32_16x16x32_bf16 v[112:115], v[202:205], v[160:163], 0
	v_mfma_f32_16x16x32_bf16 v[100:103], v[194:197], v[168:171], 0
	v_mfma_f32_16x16x32_bf16 v[96:99], v[202:205], v[168:171], 0
	v_mfma_f32_16x16x32_bf16 v[84:87], v[194:197], v[176:179], 0
	v_mfma_f32_16x16x32_bf16 v[80:83], v[202:205], v[176:179], 0
	v_mfma_f32_16x16x32_bf16 v[68:71], v[194:197], v[184:187], 0
	v_mfma_f32_16x16x32_bf16 v[64:67], v[202:205], v[184:187], 0
	v_mfma_f32_16x16x32_bf16 v[116:119], v[198:201], v[164:167], v[116:119]
	v_mfma_f32_16x16x32_bf16 v[112:115], v[206:209], v[164:167], v[112:115]
	v_mfma_f32_16x16x32_bf16 v[100:103], v[198:201], v[172:175], v[100:103]
	v_mfma_f32_16x16x32_bf16 v[96:99], v[206:209], v[172:175], v[96:99]
	v_mfma_f32_16x16x32_bf16 v[84:87], v[198:201], v[180:183], v[84:87]
	v_mfma_f32_16x16x32_bf16 v[80:83], v[206:209], v[180:183], v[80:83]
	v_mfma_f32_16x16x32_bf16 v[68:71], v[198:201], v[188:191], v[68:71]
	v_mfma_f32_16x16x32_bf16 v[64:67], v[206:209], v[188:191], v[64:67]
	s_setprio 0
	s_barrier
	ds_read_b128 v[160:163], v142 offset:16384
	ds_read_b128 v[164:167], v142 offset:17408
	ds_read_b128 v[168:171], v142 offset:18432
	ds_read_b128 v[172:175], v142 offset:19456
	ds_read_b128 v[176:179], v142 offset:20480
	ds_read_b128 v[180:183], v142 offset:21504
	ds_read_b128 v[184:187], v142 offset:22528
	ds_read_b128 v[188:191], v142 offset:23552
	s_add_i32 s71, 0, 0x14000
	s_add_i32 s9, s9, s50
	v_lshl_add_u64 v[138:139], s[4:5], 0, v[192:193]
	s_mov_b32 m0, s9
	v_lshl_add_u64 v[210:211], s[4:5], 0, v[128:129]
	global_load_lds_dwordx4 v[138:139], off
	s_add_i32 m0, s9, 0x2000
	s_nop 0
	global_load_lds_dwordx4 v[210:211], off
	s_mov_b32 m0, s39
	v_lshl_add_u64 v[212:213], s[48:49], 0, v[132:133]
	global_load_lds_dwordx4 v[212:213], off
	v_lshl_add_u64 v[214:215], s[48:49], 0, v[130:131]
	s_mov_b32 m0, s54
	s_nop 0
	global_load_lds_dwordx4 v[214:215], off
	s_add_u32 s46, s4, 0x80000
	s_addc_u32 s47, s5, 0
	s_add_i32 s9, s71, s50
	v_lshl_add_u64 v[218:219], s[46:47], 0, v[192:193]
	s_mov_b32 m0, s9
	s_nop 0
	global_load_lds_dwordx4 v[218:219], off
	v_lshl_add_u64 v[220:221], s[46:47], 0, v[128:129]
	s_add_i32 m0, s9, 0x2000
	s_nop 0
	global_load_lds_dwordx4 v[220:221], off
	s_cmp_eq_u32 s99, 1
	s_cbranch_scc1 .Lrw256_2r
	s_waitcnt vmcnt(8)
	s_branch .Lrw256_2d

.Lrw256_2d:
	s_waitcnt lgkmcnt(0)
	s_barrier
	s_setprio 1
	v_mfma_f32_16x16x32_bf16 v[60:63], v[144:147], v[160:163], 0
	v_mfma_f32_16x16x32_bf16 v[56:59], v[152:155], v[160:163], 0
	v_mfma_f32_16x16x32_bf16 v[44:47], v[144:147], v[168:171], 0
	v_mfma_f32_16x16x32_bf16 v[40:43], v[152:155], v[168:171], 0
	v_mfma_f32_16x16x32_bf16 v[28:31], v[144:147], v[176:179], 0
	v_mfma_f32_16x16x32_bf16 v[24:27], v[152:155], v[176:179], 0
	v_mfma_f32_16x16x32_bf16 v[12:15], v[144:147], v[184:187], 0
	v_mfma_f32_16x16x32_bf16 v[8:11], v[152:155], v[184:187], 0
	v_mfma_f32_16x16x32_bf16 v[60:63], v[148:151], v[164:167], v[60:63]
	v_mfma_f32_16x16x32_bf16 v[56:59], v[156:159], v[164:167], v[56:59]
	v_mfma_f32_16x16x32_bf16 v[44:47], v[148:151], v[172:175], v[44:47]
	v_mfma_f32_16x16x32_bf16 v[40:43], v[156:159], v[172:175], v[40:43]
	v_mfma_f32_16x16x32_bf16 v[28:31], v[148:151], v[180:183], v[28:31]
	v_mfma_f32_16x16x32_bf16 v[24:27], v[156:159], v[180:183], v[24:27]
	v_mfma_f32_16x16x32_bf16 v[12:15], v[148:151], v[188:191], v[12:15]
	v_mfma_f32_16x16x32_bf16 v[8:11], v[156:159], v[188:191], v[8:11]
	v_mfma_f32_16x16x32_bf16 v[52:55], v[194:197], v[160:163], 0
	v_mfma_f32_16x16x32_bf16 v[48:51], v[202:205], v[160:163], 0
	v_mfma_f32_16x16x32_bf16 v[36:39], v[194:197], v[168:171], 0
	v_mfma_f32_16x16x32_bf16 v[32:35], v[202:205], v[168:171], 0
	v_mfma_f32_16x16x32_bf16 v[20:23], v[194:197], v[176:179], 0
	v_mfma_f32_16x16x32_bf16 v[16:19], v[202:205], v[176:179], 0
	v_mfma_f32_16x16x32_bf16 v[4:7], v[194:197], v[184:187], 0
	v_mfma_f32_16x16x32_bf16 v[0:3], v[202:205], v[184:187], 0
	v_mfma_f32_16x16x32_bf16 v[52:55], v[198:201], v[164:167], v[52:55]
	v_mfma_f32_16x16x32_bf16 v[48:51], v[206:209], v[164:167], v[48:51]
	v_mfma_f32_16x16x32_bf16 v[36:39], v[198:201], v[172:175], v[36:39]
	v_mfma_f32_16x16x32_bf16 v[32:35], v[206:209], v[172:175], v[32:35]
	v_mfma_f32_16x16x32_bf16 v[20:23], v[198:201], v[180:183], v[20:23]
	v_mfma_f32_16x16x32_bf16 v[16:19], v[206:209], v[180:183], v[16:19]
	v_mfma_f32_16x16x32_bf16 v[4:7], v[198:201], v[188:191], v[4:7]
	v_mfma_f32_16x16x32_bf16 v[0:3], v[206:209], v[188:191], v[0:3]
	s_setprio 0
	s_barrier
	v_add_u32_e32 v143, 0x18000, v141
	ds_read_b128 v[144:147], v143
	ds_read_b128 v[148:151], v143 offset:1024
	ds_read_b128 v[152:155], v143 offset:2048
	ds_read_b128 v[156:159], v143 offset:3072
	ds_read_b128 v[160:163], v142 offset:32768
	ds_read_b128 v[164:167], v142 offset:33792
	ds_read_b128 v[168:171], v142 offset:34816
	ds_read_b128 v[172:175], v142 offset:35840
	ds_read_b128 v[176:179], v142 offset:36864
	ds_read_b128 v[180:183], v142 offset:37888
	ds_read_b128 v[184:187], v142 offset:38912
	ds_read_b128 v[188:191], v142 offset:39936
	v_add_u32_e32 v143, 0x1c000, v141
	ds_read_b128 v[194:197], v143
	ds_read_b128 v[198:201], v143 offset:1024
	ds_read_b128 v[202:205], v143 offset:2048
	ds_read_b128 v[206:209], v143 offset:3072
	s_add_i32 s9, 0, 0x18000
	s_add_u32 s46, s48, 0x80000
	s_addc_u32 s47, s49, 0
	s_mov_b32 m0, s55
	v_lshl_add_u64 v[218:219], s[46:47], 0, v[132:133]
	global_load_lds_dwordx4 v[218:219], off
	v_lshl_add_u64 v[220:221], s[46:47], 0, v[130:131]
	s_mov_b32 m0, s58
	s_nop 0
	global_load_lds_dwordx4 v[220:221], off
	s_waitcnt vmcnt(8)
	s_waitcnt lgkmcnt(0)
	s_barrier
	s_setprio 1
	v_mfma_f32_16x16x32_bf16 v[124:127], v[144:147], v[160:163], v[124:127]
	v_mfma_f32_16x16x32_bf16 v[120:123], v[152:155], v[160:163], v[120:123]
	v_mfma_f32_16x16x32_bf16 v[108:111], v[144:147], v[168:171], v[108:111]
	v_mfma_f32_16x16x32_bf16 v[104:107], v[152:155], v[168:171], v[104:107]
	v_mfma_f32_16x16x32_bf16 v[92:95], v[144:147], v[176:179], v[92:95]
	v_mfma_f32_16x16x32_bf16 v[88:91], v[152:155], v[176:179], v[88:91]
	v_mfma_f32_16x16x32_bf16 v[76:79], v[144:147], v[184:187], v[76:79]
	v_mfma_f32_16x16x32_bf16 v[72:75], v[152:155], v[184:187], v[72:75]
	v_mfma_f32_16x16x32_bf16 v[124:127], v[148:151], v[164:167], v[124:127]
	v_mfma_f32_16x16x32_bf16 v[120:123], v[156:159], v[164:167], v[120:123]
	v_mfma_f32_16x16x32_bf16 v[108:111], v[148:151], v[172:175], v[108:111]
	v_mfma_f32_16x16x32_bf16 v[104:107], v[156:159], v[172:175], v[104:107]
	v_mfma_f32_16x16x32_bf16 v[92:95], v[148:151], v[180:183], v[92:95]
	v_mfma_f32_16x16x32_bf16 v[88:91], v[156:159], v[180:183], v[88:91]
	v_mfma_f32_16x16x32_bf16 v[76:79], v[148:151], v[188:191], v[76:79]
	v_mfma_f32_16x16x32_bf16 v[72:75], v[156:159], v[188:191], v[72:75]
	v_mfma_f32_16x16x32_bf16 v[116:119], v[194:197], v[160:163], v[116:119]
	v_mfma_f32_16x16x32_bf16 v[112:115], v[202:205], v[160:163], v[112:115]
	v_mfma_f32_16x16x32_bf16 v[100:103], v[194:197], v[168:171], v[100:103]
	v_mfma_f32_16x16x32_bf16 v[96:99], v[202:205], v[168:171], v[96:99]
	v_mfma_f32_16x16x32_bf16 v[84:87], v[194:197], v[176:179], v[84:87]
	v_mfma_f32_16x16x32_bf16 v[80:83], v[202:205], v[176:179], v[80:83]
	v_mfma_f32_16x16x32_bf16 v[68:71], v[194:197], v[184:187], v[68:71]
	v_mfma_f32_16x16x32_bf16 v[64:67], v[202:205], v[184:187], v[64:67]
	v_mfma_f32_16x16x32_bf16 v[116:119], v[198:201], v[164:167], v[116:119]
	v_mfma_f32_16x16x32_bf16 v[112:115], v[206:209], v[164:167], v[112:115]
	v_mfma_f32_16x16x32_bf16 v[100:103], v[198:201], v[172:175], v[100:103]
	v_mfma_f32_16x16x32_bf16 v[96:99], v[206:209], v[172:175], v[96:99]
	v_mfma_f32_16x16x32_bf16 v[84:87], v[198:201], v[180:183], v[84:87]
	v_mfma_f32_16x16x32_bf16 v[80:83], v[206:209], v[180:183], v[80:83]
	v_mfma_f32_16x16x32_bf16 v[68:71], v[198:201], v[188:191], v[68:71]
	v_mfma_f32_16x16x32_bf16 v[64:67], v[206:209], v[188:191], v[64:67]
	s_setprio 0
	s_barrier
	ds_read_b128 v[160:163], v142 offset:49152
	ds_read_b128 v[164:167], v142 offset:50176
	ds_read_b128 v[168:171], v142 offset:51200
	ds_read_b128 v[172:175], v142 offset:52224
	ds_read_b128 v[176:179], v142 offset:53248
	ds_read_b128 v[180:183], v142 offset:54272
	ds_read_b128 v[184:187], v142 offset:55296
	ds_read_b128 v[188:191], v142 offset:56320
	s_add_i32 s46, 0, 0x1c000
	s_add_i32 s9, s9, s50
	v_lshl_add_u64 v[138:139], v[138:139], 0, s[72:73]
	s_mov_b32 m0, s9
	s_nop 0
	global_load_lds_dwordx4 v[138:139], off
	v_lshl_add_u64 v[138:139], v[210:211], 0, s[72:73]
	s_add_i32 m0, s9, 0x2000
	s_nop 0
	global_load_lds_dwordx4 v[138:139], off
	s_mov_b32 m0, s59
	v_lshl_add_u64 v[138:139], v[212:213], 0, s[72:73]
	global_load_lds_dwordx4 v[138:139], off
	v_lshl_add_u64 v[138:139], v[214:215], 0, s[72:73]
	s_mov_b32 m0, s62
	s_nop 0
	global_load_lds_dwordx4 v[138:139], off
	s_add_u32 s4, s4, 0x80080
	s_addc_u32 s5, s5, 0
	s_add_i32 s9, s46, s50
	v_lshl_add_u64 v[138:139], s[4:5], 0, v[192:193]
	s_mov_b32 m0, s9
	s_nop 0
	global_load_lds_dwordx4 v[138:139], off
	v_lshl_add_u64 v[138:139], s[4:5], 0, v[128:129]
	s_add_i32 m0, s9, 0x2000
	s_nop 0
	global_load_lds_dwordx4 v[138:139], off
	s_waitcnt vmcnt(8)
	s_waitcnt lgkmcnt(0)
	s_barrier
	s_setprio 1
	v_mfma_f32_16x16x32_bf16 v[60:63], v[144:147], v[160:163], v[60:63]
	v_mfma_f32_16x16x32_bf16 v[56:59], v[152:155], v[160:163], v[56:59]
	v_mfma_f32_16x16x32_bf16 v[44:47], v[144:147], v[168:171], v[44:47]
	v_mfma_f32_16x16x32_bf16 v[40:43], v[152:155], v[168:171], v[40:43]
	v_mfma_f32_16x16x32_bf16 v[28:31], v[144:147], v[176:179], v[28:31]
	v_mfma_f32_16x16x32_bf16 v[24:27], v[152:155], v[176:179], v[24:27]
	v_mfma_f32_16x16x32_bf16 v[12:15], v[144:147], v[184:187], v[12:15]
	v_mfma_f32_16x16x32_bf16 v[8:11], v[152:155], v[184:187], v[8:11]
	v_mfma_f32_16x16x32_bf16 v[60:63], v[148:151], v[164:167], v[60:63]
	v_mfma_f32_16x16x32_bf16 v[56:59], v[156:159], v[164:167], v[56:59]
	v_mfma_f32_16x16x32_bf16 v[44:47], v[148:151], v[172:175], v[44:47]
	v_mfma_f32_16x16x32_bf16 v[40:43], v[156:159], v[172:175], v[40:43]
	v_mfma_f32_16x16x32_bf16 v[28:31], v[148:151], v[180:183], v[28:31]
	v_mfma_f32_16x16x32_bf16 v[24:27], v[156:159], v[180:183], v[24:27]
	v_mfma_f32_16x16x32_bf16 v[12:15], v[148:151], v[188:191], v[12:15]
	v_mfma_f32_16x16x32_bf16 v[8:11], v[156:159], v[188:191], v[8:11]
	v_mfma_f32_16x16x32_bf16 v[52:55], v[194:197], v[160:163], v[52:55]
	v_mfma_f32_16x16x32_bf16 v[48:51], v[202:205], v[160:163], v[48:51]
	v_mfma_f32_16x16x32_bf16 v[36:39], v[194:197], v[168:171], v[36:39]
	v_mfma_f32_16x16x32_bf16 v[32:35], v[202:205], v[168:171], v[32:35]
	v_mfma_f32_16x16x32_bf16 v[20:23], v[194:197], v[176:179], v[20:23]
	v_mfma_f32_16x16x32_bf16 v[16:19], v[202:205], v[176:179], v[16:19]
	v_mfma_f32_16x16x32_bf16 v[4:7], v[194:197], v[184:187], v[4:7]
	v_mfma_f32_16x16x32_bf16 v[0:3], v[202:205], v[184:187], v[0:3]
	v_mfma_f32_16x16x32_bf16 v[52:55], v[198:201], v[164:167], v[52:55]
	v_mfma_f32_16x16x32_bf16 v[48:51], v[206:209], v[164:167], v[48:51]
	v_mfma_f32_16x16x32_bf16 v[36:39], v[198:201], v[172:175], v[36:39]
	v_mfma_f32_16x16x32_bf16 v[32:35], v[206:209], v[172:175], v[32:35]
	v_mfma_f32_16x16x32_bf16 v[20:23], v[198:201], v[180:183], v[20:23]
	v_mfma_f32_16x16x32_bf16 v[16:19], v[206:209], v[180:183], v[16:19]
	v_mfma_f32_16x16x32_bf16 v[4:7], v[198:201], v[188:191], v[4:7]
	v_mfma_f32_16x16x32_bf16 v[0:3], v[206:209], v[188:191], v[0:3]
	s_setprio 0
	s_add_i32 s69, s69, 2
	s_add_u32 s2, s2, 0x100
	s_addc_u32 s3, s3, 0
	s_add_u32 s15, s15, 0x100
	s_addc_u32 s29, s29, 0
	s_cmp_gt_u32 s69, 29
	s_barrier
	s_cbranch_scc0 .LBB0_256
	s_branch .Lpeel_done_256

.Lpeel_done_256:
	s_lshl_b32 s2, s38, 8
	v_mov_b32 v138, v140
	s_add_i32 s2, s2, s63
	v_and_or_b32 v144, v138, 15, s2
	s_lshl_b32 s2, s67, 8
	v_ashrrev_i32_e32 v138, 1, v138
	v_max_f32_e32 v120, v120, v120
	s_or_b32 s2, s2, s64
	v_and_b32_e32 v138, -8, v138
	v_max_f32_e32 v120, 0, v120
	v_max_f32_e32 v121, v121, v121
	v_max_f32_e32 v122, v122, v122
	v_add_u32_e32 v138, s2, v138
	v_ashrrev_i32_e32 v145, 31, v144
	v_readlane_b32 s2, v252, 63
	v_mul_f32_e32 v143, v120, v120
	v_max_f32_e32 v120, v125, v125
	v_max_f32_e32 v121, 0, v121
	v_max_f32_e32 v122, 0, v122
	v_ashrrev_i32_e32 v139, 31, v138
	v_lshlrev_b64 v[146:147], 14, v[144:145]
	v_readlane_b32 s3, v253, 0
	v_max_f32_e32 v124, v124, v124
	v_max_f32_e32 v120, 0, v120
	v_mul_f32_e32 v125, v121, v121
	v_max_f32_e32 v121, v126, v126
	v_mul_f32_e32 v126, v122, v122
	v_max_f32_e32 v122, v127, v127
	v_max_f32_e32 v123, v123, v123
	v_lshl_add_u64 v[146:147], s[2:3], 0, v[146:147]
	v_lshlrev_b64 v[148:149], 1, v[138:139]
	v_max_f32_e32 v124, 0, v124
	v_mul_f32_e32 v120, v120, v120
	v_max_f32_e32 v121, 0, v121
	v_max_f32_e32 v122, 0, v122
	v_max_f32_e32 v123, 0, v123
	v_max_f32_e32 v112, v112, v112
	v_lshl_add_u64 v[138:139], v[146:147], 0, v[148:149]
	v_mul_f32_e32 v124, v124, v124
	v_mul_f32_e32 v121, v121, v121
	v_mul_f32_e32 v122, v122, v122
	v_mul_f32_e32 v123, v123, v123
	v_cvt_pk_bf16_f32 v120, v124, v120
	v_max_f32_e32 v112, 0, v112
	v_max_f32_e32 v113, v113, v113
	v_max_f32_e32 v114, v114, v114
	v_cvt_pk_bf16_f32 v121, v121, v122
	v_cvt_pk_bf16_f32 v122, v143, v125
	v_cvt_pk_bf16_f32 v123, v126, v123
	global_store_dwordx4 v[138:139], v[120:123], off
	v_max_f32_e32 v113, 0, v113
	v_max_f32_e32 v114, 0, v114
	v_mul_f32_e32 v120, v112, v112
	v_max_f32_e32 v112, v117, v117
	v_max_f32_e32 v116, v116, v116
	v_max_f32_e32 v112, 0, v112
	v_mul_f32_e32 v117, v113, v113
	v_max_f32_e32 v113, v118, v118
	v_mul_f32_e32 v118, v114, v114
	v_max_f32_e32 v114, v119, v119
	v_max_f32_e32 v115, v115, v115
	v_max_f32_e32 v116, 0, v116
	v_mul_f32_e32 v112, v112, v112
	v_max_f32_e32 v113, 0, v113
	v_max_f32_e32 v114, 0, v114
	v_max_f32_e32 v115, 0, v115
	v_mul_f32_e32 v116, v116, v116
	v_mul_f32_e32 v113, v113, v113
	v_mul_f32_e32 v114, v114, v114
	v_mul_f32_e32 v115, v115, v115
	v_cvt_pk_bf16_f32 v112, v116, v112
	v_max_f32_e32 v104, v104, v104
	v_cvt_pk_bf16_f32 v113, v113, v114
	v_cvt_pk_bf16_f32 v114, v120, v117
	v_cvt_pk_bf16_f32 v115, v118, v115
	global_store_dwordx4 v[138:139], v[112:115], off offset:256
	v_max_f32_e32 v104, 0, v104
	v_max_f32_e32 v105, v105, v105
	v_or_b32_e32 v112, 16, v144
	v_max_f32_e32 v106, v106, v106
	v_ashrrev_i32_e32 v113, 31, v112
	v_mul_f32_e32 v114, v104, v104
	v_max_f32_e32 v104, v109, v109
	v_max_f32_e32 v105, 0, v105
	v_max_f32_e32 v106, 0, v106
	v_lshlrev_b64 v[112:113], 14, v[112:113]
	v_max_f32_e32 v108, v108, v108
	v_max_f32_e32 v104, 0, v104
	v_mul_f32_e32 v109, v105, v105
	v_max_f32_e32 v105, v110, v110
	v_mul_f32_e32 v110, v106, v106
	v_max_f32_e32 v106, v111, v111
	v_max_f32_e32 v107, v107, v107
	v_lshl_add_u64 v[112:113], s[2:3], 0, v[112:113]
	v_max_f32_e32 v108, 0, v108
	v_mul_f32_e32 v104, v104, v104
	v_max_f32_e32 v105, 0, v105
	v_max_f32_e32 v106, 0, v106
	v_max_f32_e32 v107, 0, v107
	v_max_f32_e32 v96, v96, v96
	v_lshl_add_u64 v[112:113], v[112:113], 0, v[148:149]
	v_mul_f32_e32 v108, v108, v108
	v_mul_f32_e32 v105, v105, v105
	v_mul_f32_e32 v106, v106, v106
	v_mul_f32_e32 v107, v107, v107
	v_cvt_pk_bf16_f32 v104, v108, v104
	v_max_f32_e32 v96, 0, v96
	v_max_f32_e32 v97, v97, v97
	v_max_f32_e32 v98, v98, v98
	v_cvt_pk_bf16_f32 v105, v105, v106
	v_cvt_pk_bf16_f32 v106, v114, v109
	v_cvt_pk_bf16_f32 v107, v110, v107
	global_store_dwordx4 v[112:113], v[104:107], off
	v_max_f32_e32 v97, 0, v97
	v_max_f32_e32 v98, 0, v98
	v_mul_f32_e32 v104, v96, v96
	v_max_f32_e32 v96, v101, v101
	v_max_f32_e32 v100, v100, v100
	v_max_f32_e32 v96, 0, v96
	v_mul_f32_e32 v101, v97, v97
	v_max_f32_e32 v97, v102, v102
	v_mul_f32_e32 v102, v98, v98
	v_max_f32_e32 v98, v103, v103
	v_max_f32_e32 v99, v99, v99
	v_max_f32_e32 v100, 0, v100
	v_mul_f32_e32 v96, v96, v96
	v_max_f32_e32 v97, 0, v97
	v_max_f32_e32 v98, 0, v98
	v_max_f32_e32 v99, 0, v99
	v_mul_f32_e32 v100, v100, v100
	v_mul_f32_e32 v97, v97, v97
	v_mul_f32_e32 v98, v98, v98
	v_mul_f32_e32 v99, v99, v99
	v_cvt_pk_bf16_f32 v96, v100, v96
	v_max_f32_e32 v88, v88, v88
	v_cvt_pk_bf16_f32 v97, v97, v98
	v_cvt_pk_bf16_f32 v98, v104, v101
	v_cvt_pk_bf16_f32 v99, v102, v99
	global_store_dwordx4 v[112:113], v[96:99], off offset:256
	v_max_f32_e32 v88, 0, v88
	v_max_f32_e32 v89, v89, v89
	v_or_b32_e32 v96, 32, v144
	v_max_f32_e32 v90, v90, v90
	v_ashrrev_i32_e32 v97, 31, v96
	v_mul_f32_e32 v98, v88, v88
	v_max_f32_e32 v88, v93, v93
	v_max_f32_e32 v89, 0, v89
	v_max_f32_e32 v90, 0, v90
	v_lshlrev_b64 v[96:97], 14, v[96:97]
	v_max_f32_e32 v92, v92, v92
	v_max_f32_e32 v88, 0, v88
	v_mul_f32_e32 v93, v89, v89
	v_max_f32_e32 v89, v94, v94
	v_mul_f32_e32 v94, v90, v90
	v_max_f32_e32 v90, v95, v95
	v_max_f32_e32 v91, v91, v91
	v_lshl_add_u64 v[96:97], s[2:3], 0, v[96:97]
	v_max_f32_e32 v92, 0, v92
	v_mul_f32_e32 v88, v88, v88
	v_max_f32_e32 v89, 0, v89
	v_max_f32_e32 v90, 0, v90
	v_max_f32_e32 v91, 0, v91
	v_max_f32_e32 v80, v80, v80
	v_lshl_add_u64 v[96:97], v[96:97], 0, v[148:149]
	v_mul_f32_e32 v92, v92, v92
	v_mul_f32_e32 v89, v89, v89
	v_mul_f32_e32 v90, v90, v90
	v_mul_f32_e32 v91, v91, v91
	v_cvt_pk_bf16_f32 v88, v92, v88
	v_max_f32_e32 v80, 0, v80
	v_max_f32_e32 v81, v81, v81
	v_max_f32_e32 v82, v82, v82
	v_cvt_pk_bf16_f32 v89, v89, v90
	v_cvt_pk_bf16_f32 v90, v98, v93
	v_cvt_pk_bf16_f32 v91, v94, v91
	global_store_dwordx4 v[96:97], v[88:91], off
	v_max_f32_e32 v81, 0, v81
	v_max_f32_e32 v82, 0, v82
	v_mul_f32_e32 v88, v80, v80
	v_max_f32_e32 v80, v85, v85
	v_max_f32_e32 v84, v84, v84
	v_max_f32_e32 v80, 0, v80
	v_mul_f32_e32 v85, v81, v81
	v_max_f32_e32 v81, v86, v86
	v_mul_f32_e32 v86, v82, v82
	v_max_f32_e32 v82, v87, v87
	v_max_f32_e32 v83, v83, v83
	v_max_f32_e32 v84, 0, v84
	v_mul_f32_e32 v80, v80, v80
	v_max_f32_e32 v81, 0, v81
	v_max_f32_e32 v82, 0, v82
	v_max_f32_e32 v83, 0, v83
	v_mul_f32_e32 v84, v84, v84
	v_mul_f32_e32 v81, v81, v81
	v_mul_f32_e32 v82, v82, v82
	v_mul_f32_e32 v83, v83, v83
	v_cvt_pk_bf16_f32 v80, v84, v80
	v_max_f32_e32 v72, v72, v72
	v_cvt_pk_bf16_f32 v81, v81, v82
	v_cvt_pk_bf16_f32 v82, v88, v85
	v_cvt_pk_bf16_f32 v83, v86, v83
	global_store_dwordx4 v[96:97], v[80:83], off offset:256
	v_max_f32_e32 v72, 0, v72
	v_max_f32_e32 v73, v73, v73
	v_or_b32_e32 v80, 48, v144
	v_max_f32_e32 v74, v74, v74
	v_ashrrev_i32_e32 v81, 31, v80
	v_mul_f32_e32 v82, v72, v72
	v_max_f32_e32 v72, v77, v77
	v_max_f32_e32 v73, 0, v73
	v_max_f32_e32 v74, 0, v74
	v_lshlrev_b64 v[80:81], 14, v[80:81]
	v_max_f32_e32 v76, v76, v76
	v_max_f32_e32 v72, 0, v72
	v_mul_f32_e32 v77, v73, v73
	v_max_f32_e32 v73, v78, v78
	v_mul_f32_e32 v78, v74, v74
	v_max_f32_e32 v74, v79, v79
	v_max_f32_e32 v75, v75, v75
	v_lshl_add_u64 v[80:81], s[2:3], 0, v[80:81]
	v_max_f32_e32 v76, 0, v76
	v_mul_f32_e32 v72, v72, v72
	v_max_f32_e32 v73, 0, v73
	v_max_f32_e32 v74, 0, v74
	v_max_f32_e32 v75, 0, v75
	v_max_f32_e32 v64, v64, v64
	v_max_f32_e32 v65, v65, v65
	v_max_f32_e32 v66, v66, v66
	v_lshl_add_u64 v[80:81], v[80:81], 0, v[148:149]
	v_mul_f32_e32 v76, v76, v76
	v_mul_f32_e32 v73, v73, v73
	v_mul_f32_e32 v74, v74, v74
	v_mul_f32_e32 v75, v75, v75
	v_cvt_pk_bf16_f32 v72, v76, v72
	v_max_f32_e32 v64, 0, v64
	v_max_f32_e32 v65, 0, v65
	v_max_f32_e32 v66, 0, v66
	v_cvt_pk_bf16_f32 v73, v73, v74
	v_cvt_pk_bf16_f32 v74, v82, v77
	v_cvt_pk_bf16_f32 v75, v78, v75
	global_store_dwordx4 v[80:81], v[72:75], off
	v_max_f32_e32 v68, v68, v68
	v_max_f32_e32 v67, v67, v67
	v_mul_f32_e32 v72, v64, v64
	v_max_f32_e32 v64, v69, v69
	v_mul_f32_e32 v69, v65, v65
	v_max_f32_e32 v65, v70, v70
	v_mul_f32_e32 v70, v66, v66
	v_max_f32_e32 v66, v71, v71
	v_max_f32_e32 v64, 0, v64
	v_max_f32_e32 v65, 0, v65
	v_max_f32_e32 v66, 0, v66
	v_max_f32_e32 v68, 0, v68
	v_mul_f32_e32 v64, v64, v64
	v_mul_f32_e32 v65, v65, v65
	v_max_f32_e32 v67, 0, v67
	v_mul_f32_e32 v66, v66, v66
	v_max_f32_e32 v56, v56, v56
	v_mul_f32_e32 v68, v68, v68
	v_mul_f32_e32 v67, v67, v67
	v_cvt_pk_bf16_f32 v64, v68, v64
	v_cvt_pk_bf16_f32 v65, v65, v66
	v_cvt_pk_bf16_f32 v66, v72, v69
	v_max_f32_e32 v56, 0, v56
	v_max_f32_e32 v57, v57, v57
	v_max_f32_e32 v58, v58, v58
	v_cvt_pk_bf16_f32 v67, v70, v67
	global_store_dwordx4 v[80:81], v[64:67], off offset:256
	v_max_f32_e32 v60, v60, v60
	v_max_f32_e32 v57, 0, v57
	v_mul_f32_e32 v66, v56, v56
	v_max_f32_e32 v56, v61, v61
	v_max_f32_e32 v58, 0, v58
	s_mov_b64 s[2:3], 0x200000
	v_max_f32_e32 v60, 0, v60
	v_max_f32_e32 v56, 0, v56
	v_mul_f32_e32 v61, v57, v57
	v_max_f32_e32 v57, v62, v62
	v_mul_f32_e32 v62, v58, v58
	v_max_f32_e32 v58, v63, v63
	v_lshl_add_u64 v[64:65], v[138:139], 0, s[2:3]
	v_mul_f32_e32 v60, v60, v60
	v_mul_f32_e32 v56, v56, v56
	v_max_f32_e32 v57, 0, v57
	v_max_f32_e32 v58, 0, v58
	v_max_f32_e32 v59, v59, v59
	s_mov_b32 s2, 0x200000
	v_mul_f32_e32 v57, v57, v57
	v_max_f32_e32 v59, 0, v59
	v_mul_f32_e32 v58, v58, v58
	v_cvt_pk_bf16_f32 v56, v60, v56
	v_add_co_u32_e32 v60, vcc, s2, v138
	v_max_f32_e32 v48, v48, v48
	v_max_f32_e32 v49, v49, v49
	v_max_f32_e32 v50, v50, v50
	v_mul_f32_e32 v59, v59, v59
	v_cvt_pk_bf16_f32 v57, v57, v58
	v_cvt_pk_bf16_f32 v58, v66, v61
	v_addc_co_u32_e32 v61, vcc, 0, v139, vcc
	v_max_f32_e32 v48, 0, v48
	v_max_f32_e32 v49, 0, v49
	v_max_f32_e32 v50, 0, v50
	v_cvt_pk_bf16_f32 v59, v62, v59
	global_store_dwordx4 v[60:61], v[56:59], off
	v_max_f32_e32 v52, v52, v52
	v_max_f32_e32 v51, v51, v51
	v_mul_f32_e32 v56, v48, v48
	v_max_f32_e32 v48, v53, v53
	v_mul_f32_e32 v53, v49, v49
	v_max_f32_e32 v49, v54, v54
	v_mul_f32_e32 v54, v50, v50
	v_max_f32_e32 v50, v55, v55
	v_max_f32_e32 v48, 0, v48
	v_max_f32_e32 v49, 0, v49
	v_max_f32_e32 v50, 0, v50
	v_max_f32_e32 v52, 0, v52
	v_mul_f32_e32 v48, v48, v48
	v_mul_f32_e32 v49, v49, v49
	v_max_f32_e32 v51, 0, v51
	v_mul_f32_e32 v50, v50, v50
	v_max_f32_e32 v40, v40, v40
	v_mul_f32_e32 v52, v52, v52
	v_mul_f32_e32 v51, v51, v51
	v_cvt_pk_bf16_f32 v48, v52, v48
	v_cvt_pk_bf16_f32 v49, v49, v50
	v_cvt_pk_bf16_f32 v50, v56, v53
	v_max_f32_e32 v40, 0, v40
	v_max_f32_e32 v41, v41, v41
	v_max_f32_e32 v42, v42, v42
	v_cvt_pk_bf16_f32 v51, v54, v51
	global_store_dwordx4 v[64:65], v[48:51], off offset:256
	v_max_f32_e32 v44, v44, v44
	v_max_f32_e32 v41, 0, v41
	v_mul_f32_e32 v50, v40, v40
	v_max_f32_e32 v40, v45, v45
	v_max_f32_e32 v42, 0, v42
	s_mov_b64 s[2:3], 0x240000
	v_max_f32_e32 v44, 0, v44
	v_max_f32_e32 v40, 0, v40
	v_mul_f32_e32 v45, v41, v41
	v_max_f32_e32 v41, v46, v46
	v_mul_f32_e32 v46, v42, v42
	v_max_f32_e32 v42, v47, v47
	v_lshl_add_u64 v[48:49], v[138:139], 0, s[2:3]
	v_mul_f32_e32 v44, v44, v44
	v_mul_f32_e32 v40, v40, v40
	v_max_f32_e32 v41, 0, v41
	v_max_f32_e32 v42, 0, v42
	v_max_f32_e32 v43, v43, v43
	s_mov_b32 s2, 0x240000
	v_mul_f32_e32 v41, v41, v41
	v_max_f32_e32 v43, 0, v43
	v_mul_f32_e32 v42, v42, v42
	v_cvt_pk_bf16_f32 v40, v44, v40
	v_add_co_u32_e32 v44, vcc, s2, v138
	v_max_f32_e32 v32, v32, v32
	v_max_f32_e32 v33, v33, v33
	v_max_f32_e32 v34, v34, v34
	v_mul_f32_e32 v43, v43, v43
	v_cvt_pk_bf16_f32 v41, v41, v42
	v_cvt_pk_bf16_f32 v42, v50, v45
	v_addc_co_u32_e32 v45, vcc, 0, v139, vcc
	v_max_f32_e32 v32, 0, v32
	v_max_f32_e32 v33, 0, v33
	v_max_f32_e32 v34, 0, v34
	v_cvt_pk_bf16_f32 v43, v46, v43
	global_store_dwordx4 v[44:45], v[40:43], off
	v_max_f32_e32 v36, v36, v36
	v_max_f32_e32 v35, v35, v35
	v_mul_f32_e32 v40, v32, v32
	v_max_f32_e32 v32, v37, v37
	v_mul_f32_e32 v37, v33, v33
	v_max_f32_e32 v33, v38, v38
	v_mul_f32_e32 v38, v34, v34
	v_max_f32_e32 v34, v39, v39
	v_max_f32_e32 v32, 0, v32
	v_max_f32_e32 v33, 0, v33
	v_max_f32_e32 v34, 0, v34
	v_max_f32_e32 v36, 0, v36
	v_mul_f32_e32 v32, v32, v32
	v_mul_f32_e32 v33, v33, v33
	v_max_f32_e32 v35, 0, v35
	v_mul_f32_e32 v34, v34, v34
	v_max_f32_e32 v24, v24, v24
	v_mul_f32_e32 v36, v36, v36
	v_mul_f32_e32 v35, v35, v35
	v_cvt_pk_bf16_f32 v32, v36, v32
	v_cvt_pk_bf16_f32 v33, v33, v34
	v_cvt_pk_bf16_f32 v34, v40, v37
	v_max_f32_e32 v24, 0, v24
	v_max_f32_e32 v25, v25, v25
	v_max_f32_e32 v26, v26, v26
	v_cvt_pk_bf16_f32 v35, v38, v35
	global_store_dwordx4 v[48:49], v[32:35], off offset:256
	v_max_f32_e32 v28, v28, v28
	v_max_f32_e32 v25, 0, v25
	v_mul_f32_e32 v34, v24, v24
	v_max_f32_e32 v24, v29, v29
	v_max_f32_e32 v26, 0, v26
	s_mov_b64 s[2:3], 0x280000
	v_max_f32_e32 v28, 0, v28
	v_max_f32_e32 v24, 0, v24
	v_mul_f32_e32 v29, v25, v25
	v_max_f32_e32 v25, v30, v30
	v_mul_f32_e32 v30, v26, v26
	v_max_f32_e32 v26, v31, v31
	v_lshl_add_u64 v[32:33], v[138:139], 0, s[2:3]
	v_mul_f32_e32 v28, v28, v28
	v_mul_f32_e32 v24, v24, v24
	v_max_f32_e32 v25, 0, v25
	v_max_f32_e32 v26, 0, v26
	v_max_f32_e32 v27, v27, v27
	s_mov_b32 s2, 0x280000
	v_mul_f32_e32 v25, v25, v25
	v_max_f32_e32 v27, 0, v27
	v_mul_f32_e32 v26, v26, v26
	v_cvt_pk_bf16_f32 v24, v28, v24
	v_add_co_u32_e32 v28, vcc, s2, v138
	v_max_f32_e32 v16, v16, v16
	v_max_f32_e32 v17, v17, v17
	v_max_f32_e32 v18, v18, v18
	v_mul_f32_e32 v27, v27, v27
	v_cvt_pk_bf16_f32 v25, v25, v26
	v_cvt_pk_bf16_f32 v26, v34, v29
	v_addc_co_u32_e32 v29, vcc, 0, v139, vcc
	v_max_f32_e32 v16, 0, v16
	v_max_f32_e32 v17, 0, v17
	v_max_f32_e32 v18, 0, v18
	v_cvt_pk_bf16_f32 v27, v30, v27
	global_store_dwordx4 v[28:29], v[24:27], off
	v_max_f32_e32 v20, v20, v20
	v_max_f32_e32 v19, v19, v19
	v_mul_f32_e32 v24, v16, v16
	v_max_f32_e32 v16, v21, v21
	v_mul_f32_e32 v21, v17, v17
	v_max_f32_e32 v17, v22, v22
	v_mul_f32_e32 v22, v18, v18
	v_max_f32_e32 v18, v23, v23
	v_max_f32_e32 v16, 0, v16
	v_max_f32_e32 v17, 0, v17
	v_max_f32_e32 v18, 0, v18
	v_max_f32_e32 v20, 0, v20
	v_mul_f32_e32 v16, v16, v16
	v_mul_f32_e32 v17, v17, v17
	v_max_f32_e32 v19, 0, v19
	v_mul_f32_e32 v18, v18, v18
	v_max_f32_e32 v8, v8, v8
	v_mul_f32_e32 v20, v20, v20
	v_mul_f32_e32 v19, v19, v19
	v_cvt_pk_bf16_f32 v16, v20, v16
	v_cvt_pk_bf16_f32 v17, v17, v18
	v_cvt_pk_bf16_f32 v18, v24, v21
	v_max_f32_e32 v8, 0, v8
	v_max_f32_e32 v9, v9, v9
	v_max_f32_e32 v10, v10, v10
	v_cvt_pk_bf16_f32 v19, v22, v19
	global_store_dwordx4 v[32:33], v[16:19], off offset:256
	v_max_f32_e32 v12, v12, v12
	v_max_f32_e32 v9, 0, v9
	v_mul_f32_e32 v18, v8, v8
	v_max_f32_e32 v8, v13, v13
	v_max_f32_e32 v10, 0, v10
	s_mov_b64 s[2:3], 0x2c0000
	v_max_f32_e32 v12, 0, v12
	v_max_f32_e32 v8, 0, v8
	v_mul_f32_e32 v13, v9, v9
	v_max_f32_e32 v9, v14, v14
	v_mul_f32_e32 v14, v10, v10
	v_max_f32_e32 v10, v15, v15
	v_lshl_add_u64 v[16:17], v[138:139], 0, s[2:3]
	v_mul_f32_e32 v12, v12, v12
	v_mul_f32_e32 v8, v8, v8
	v_max_f32_e32 v9, 0, v9
	v_max_f32_e32 v10, 0, v10
	v_max_f32_e32 v11, v11, v11
	s_mov_b32 s2, 0x2c0000
	v_mul_f32_e32 v9, v9, v9
	v_max_f32_e32 v11, 0, v11
	v_mul_f32_e32 v10, v10, v10
	v_cvt_pk_bf16_f32 v8, v12, v8
	v_add_co_u32_e32 v12, vcc, s2, v138
	v_max_f32_e32 v0, v0, v0
	v_max_f32_e32 v1, v1, v1
	v_max_f32_e32 v2, v2, v2
	v_mul_f32_e32 v11, v11, v11
	v_cvt_pk_bf16_f32 v9, v9, v10
	v_cvt_pk_bf16_f32 v10, v18, v13
	v_addc_co_u32_e32 v13, vcc, 0, v139, vcc
	v_max_f32_e32 v0, 0, v0
	v_max_f32_e32 v1, 0, v1
	v_max_f32_e32 v2, 0, v2
	v_cvt_pk_bf16_f32 v11, v14, v11
	global_store_dwordx4 v[12:13], v[8:11], off
	v_max_f32_e32 v3, v3, v3
	v_max_f32_e32 v4, v4, v4
	v_mul_f32_e32 v8, v0, v0
	v_max_f32_e32 v0, v5, v5
	v_mul_f32_e32 v5, v1, v1
	v_max_f32_e32 v1, v6, v6
	v_mul_f32_e32 v6, v2, v2
	v_max_f32_e32 v2, v7, v7
	v_max_f32_e32 v0, 0, v0
	v_max_f32_e32 v1, 0, v1
	v_max_f32_e32 v2, 0, v2
	v_max_f32_e32 v3, 0, v3
	v_max_f32_e32 v4, 0, v4
	v_mul_f32_e32 v0, v0, v0
	v_mul_f32_e32 v1, v1, v1
	v_mul_f32_e32 v2, v2, v2
	v_mul_f32_e32 v3, v3, v3
	s_and_b64 vcc, exec, s[0:1]
	s_mov_b32 s67, s14
	s_mov_b32 s38, s28
	s_mov_b64 s[4:5], s[36:37]
	s_mov_b64 s[2:3], s[34:35]
	v_mul_f32_e32 v4, v4, v4
	v_cvt_pk_bf16_f32 v0, v4, v0
	v_cvt_pk_bf16_f32 v1, v1, v2
	v_cvt_pk_bf16_f32 v2, v8, v5
	v_cvt_pk_bf16_f32 v3, v6, v3
	global_store_dwordx4 v[16:17], v[0:3], off offset:256
	s_mov_b32 s99, 1
	s_cbranch_vccz .LBB0_253
	s_waitcnt vmcnt(0)
	v_readlane_b32 s62, v254, 59
	s_cmpk_gt_u32 s41, 0xff
	v_readlane_b32 s55, v254, 57
	v_readlane_b32 s58, v254, 58
	v_readlane_b32 s63, v254, 60
	v_readlane_b32 s59, v255, 1
	s_movk_i32 s66, 0x3000
	v_readlane_b32 s49, v255, 18
	s_cbranch_scc1 .LBB0_260
	s_barrier
